# K-loops: drop per-segment s_setprio 1/0 pair (loader half has no VALU left after saddr addressing)
# baseline (speedup 1.0000x reference)
; #define PG8_STAGE(bufoff, gbase, voff) do { _Pragma("unroll") for (int _i = 0; _i < 2; ++_i) \
;         __builtin_amdgcn_global_load_lds((const unsigned*)((const char*)(gbase) + (voff)[_i]), (PG8_LAS unsigned*)(lds + (bufoff) + ldsw + _i * 8192), 16, 0, 0); } while (0)
; #define PG8_LDA(dst, b, h) do { _Pragma("unroll") for (int m = 0; m < 4; ++m) _Pragma("unroll") for (int k = 0; k < 2; ++k) dst[m][k] = *(const PG8_LAS bf16x8*)(lds + PG8_SA(b, h) + aoff + m * 2048 + k * 1024); } while (0)
; #define PG8_LDB(dst, b, h) do { _Pragma("unroll") for (int n = 0; n < 2; ++n) _Pragma("unroll") for (int k = 0; k < 2; ++k) dst[n][k] = *(const PG8_LAS bf16x8*)(lds + PG8_SB(b, h) + boff + n * 2048 + k * 1024); } while (0)
; #define PG8_MMA(ai, bj, At, Bt) do { __builtin_amdgcn_s_setprio(1); _Pragma("unroll") for (int m = 0; m < 4; ++m) _Pragma("unroll") for (int n = 0; n < 2; ++n) _Pragma("unroll") for (int k = 0; k < 2; ++k) \
;         acc[ai][bj][m][n] = __builtin_amdgcn_mfma_f32_16x16x32_bf16(Bt[n][k], At[m][k], acc[ai][bj][m][n], 0, 0, 0); __builtin_amdgcn_s_setprio(0); } while (0)
; #define PG8_WAIT_V(n) asm volatile("s_waitcnt vmcnt(" #n ")" ::: "memory")
; #define PG8_WAIT_L(n) asm volatile("s_waitcnt lgkmcnt(" #n ")" ::: "memory")
; #define PG8_BAR __builtin_amdgcn_s_barrier()
; #define PG8_SCHED __builtin_amdgcn_sched_barrier(0)
; template <class Epi, class Sched, bool ALIGN_EPI = false, bool SP2 = false>
; __device__ __forceinline__ void gemm_phase(PG8_LAS unsigned char* lds, const Gemm g, const Sched& S, const Epi& E) {
;     ...
;             PG8_LDB(B0, 0, 0); PG8_LDB(B1, 0, 1); PG8_SCHED; PG8_LDA(At, 0, 0); PG8_STAGE(PG8_SA(1, 1), a1 + hstep, voffA);
;             PG8_WAIT_V(8); PG8_WAIT_L(0); PG8_BAR; PG8_MMA(0, 0, At, B0); PG8_MMA(0, 1, At, B1); PG8_BAR; PG8_SCHED;
;             PG8_LDA(At, 0, 1); PG8_STAGE(PG8_SB(0, 0), b2, voffB); PG8_STAGE(PG8_SB(0, 1), b2 + hstep, voffB); PG8_STAGE(PG8_SA(0, 0), a2, voffA);
;             PG8_WAIT_V(8); PG8_WAIT_L(0); PG8_BAR; PG8_MMA(1, 0, At, B0); PG8_MMA(1, 1, At, B1); PG8_BAR; PG8_SCHED;
.LBB0_136:
	ds_read_b128 v[158:161], v152
	ds_read_b128 v[162:165], v152 offset:1024
	ds_read_b128 v[166:169], v152 offset:2048
	ds_read_b128 v[170:173], v152 offset:3072
	ds_read_b128 v[174:177], v153
	ds_read_b128 v[178:181], v153 offset:1024
	ds_read_b128 v[182:185], v153 offset:2048
	ds_read_b128 v[186:189], v153 offset:3072
	s_add_u32 s64, s62, 0xfffc0080
	s_addc_u32 s65, s63, -1
	s_cmp_eq_u32 s76, 12
	s_cselect_b32 s71, s5, s65
	s_cselect_b32 s70, s26, s64
	s_cselect_b32 s65, s27, s75
	s_cselect_b32 s64, s53, s55
	s_add_i32 m0, s61, 0xc000
	ds_read_b128 v[190:193], v154
	ds_read_b128 v[194:197], v154 offset:1024
	ds_read_b128 v[198:201], v154 offset:2048
	ds_read_b128 v[206:209], v154 offset:3072
	ds_read_b128 v[210:213], v154 offset:4096
	ds_read_b128 v[214:217], v154 offset:5120
	ds_read_b128 v[218:221], v154 offset:6144
	ds_read_b128 v[222:225], v154 offset:7168
	global_load_lds_dwordx4 v138, s[62:63]
	s_add_i32 m0, s61, 0xe000
	s_nop 0
	global_load_lds_dwordx4 v140, s[62:63]
	s_waitcnt vmcnt(8)
	s_waitcnt lgkmcnt(0)
	s_barrier
	v_mfma_f32_16x16x32_bf16 v[124:127], v[158:161], v[190:193], v[124:127]
	v_mfma_f32_16x16x32_bf16 v[120:123], v[166:169], v[190:193], v[120:123]
	v_mfma_f32_16x16x32_bf16 v[108:111], v[158:161], v[198:201], v[108:111]
	v_mfma_f32_16x16x32_bf16 v[104:107], v[166:169], v[198:201], v[104:107]
	v_mfma_f32_16x16x32_bf16 v[92:95], v[158:161], v[210:213], v[92:95]
	v_mfma_f32_16x16x32_bf16 v[88:91], v[166:169], v[210:213], v[88:91]
	v_mfma_f32_16x16x32_bf16 v[76:79], v[158:161], v[218:221], v[76:79]
	v_mfma_f32_16x16x32_bf16 v[72:75], v[166:169], v[218:221], v[72:75]
	v_mfma_f32_16x16x32_bf16 v[124:127], v[162:165], v[194:197], v[124:127]
	v_mfma_f32_16x16x32_bf16 v[120:123], v[170:173], v[194:197], v[120:123]
	v_mfma_f32_16x16x32_bf16 v[108:111], v[162:165], v[206:209], v[108:111]
	v_mfma_f32_16x16x32_bf16 v[104:107], v[170:173], v[206:209], v[104:107]
	v_mfma_f32_16x16x32_bf16 v[92:95], v[162:165], v[214:217], v[92:95]
	v_mfma_f32_16x16x32_bf16 v[88:91], v[170:173], v[214:217], v[88:91]
	v_mfma_f32_16x16x32_bf16 v[76:79], v[162:165], v[222:225], v[76:79]
	v_mfma_f32_16x16x32_bf16 v[72:75], v[170:173], v[222:225], v[72:75]
	v_mfma_f32_16x16x32_bf16 v[116:119], v[174:177], v[190:193], v[116:119]
	v_mfma_f32_16x16x32_bf16 v[112:115], v[182:185], v[190:193], v[112:115]
	v_mfma_f32_16x16x32_bf16 v[100:103], v[174:177], v[198:201], v[100:103]
	v_mfma_f32_16x16x32_bf16 v[96:99], v[182:185], v[198:201], v[96:99]
	v_mfma_f32_16x16x32_bf16 v[84:87], v[174:177], v[210:213], v[84:87]
	v_mfma_f32_16x16x32_bf16 v[80:83], v[182:185], v[210:213], v[80:83]
	v_mfma_f32_16x16x32_bf16 v[68:71], v[174:177], v[218:221], v[68:71]
	v_mfma_f32_16x16x32_bf16 v[64:67], v[182:185], v[218:221], v[64:67]
	v_mfma_f32_16x16x32_bf16 v[116:119], v[178:181], v[194:197], v[116:119]
	v_mfma_f32_16x16x32_bf16 v[112:115], v[186:189], v[194:197], v[112:115]
	v_mfma_f32_16x16x32_bf16 v[100:103], v[178:181], v[206:209], v[100:103]
	v_mfma_f32_16x16x32_bf16 v[96:99], v[186:189], v[206:209], v[96:99]
	v_mfma_f32_16x16x32_bf16 v[84:87], v[178:181], v[214:217], v[84:87]
	v_mfma_f32_16x16x32_bf16 v[80:83], v[186:189], v[214:217], v[80:83]
	v_mfma_f32_16x16x32_bf16 v[68:71], v[178:181], v[222:225], v[68:71]
	v_mfma_f32_16x16x32_bf16 v[64:67], v[186:189], v[222:225], v[64:67]
	s_barrier
	s_add_i32 s77, s72, s33
	s_mov_b32 m0, s77
	ds_read_b128 v[190:193], v154 offset:16384
	ds_read_b128 v[194:197], v154 offset:17408
	ds_read_b128 v[198:201], v154 offset:18432
	ds_read_b128 v[206:209], v154 offset:19456
	ds_read_b128 v[210:213], v154 offset:20480
	ds_read_b128 v[214:217], v154 offset:21504
	ds_read_b128 v[218:221], v154 offset:22528
	ds_read_b128 v[222:225], v154 offset:23552
	global_load_lds_dwordx4 v132, s[64:65]
	s_add_i32 m0, s77, 0x2000
	s_add_u32 s98, s64, 0x80
	s_addc_u32 s99, s65, 0
	s_add_u32 s78, s64, 0x40000
	s_addc_u32 s79, s65, 0
	s_add_i32 s77, s73, s33
	global_load_lds_dwordx4 v136, s[64:65]
	s_mov_b32 m0, s77
	s_nop 0
	global_load_lds_dwordx4 v132, s[78:79]
	s_add_i32 m0, s77, 0x2000
	s_nop 0
	global_load_lds_dwordx4 v136, s[78:79]
	s_mov_b32 m0, s61
	s_nop 0
	global_load_lds_dwordx4 v130, s[70:71]
	s_mov_b32 m0, s66
	s_nop 0
	global_load_lds_dwordx4 v134, s[70:71]
	s_waitcnt vmcnt(8)
	s_waitcnt lgkmcnt(0)
	s_barrier
	v_mfma_f32_16x16x32_bf16 v[60:63], v[158:161], v[190:193], v[60:63]
	v_mfma_f32_16x16x32_bf16 v[56:59], v[166:169], v[190:193], v[56:59]
	v_mfma_f32_16x16x32_bf16 v[44:47], v[158:161], v[198:201], v[44:47]
	v_mfma_f32_16x16x32_bf16 v[40:43], v[166:169], v[198:201], v[40:43]
	v_mfma_f32_16x16x32_bf16 v[28:31], v[158:161], v[210:213], v[28:31]
	v_mfma_f32_16x16x32_bf16 v[24:27], v[166:169], v[210:213], v[24:27]
	v_mfma_f32_16x16x32_bf16 v[12:15], v[158:161], v[218:221], v[12:15]
	v_mfma_f32_16x16x32_bf16 v[8:11], v[166:169], v[218:221], v[8:11]
	v_mfma_f32_16x16x32_bf16 v[60:63], v[162:165], v[194:197], v[60:63]
	v_mfma_f32_16x16x32_bf16 v[56:59], v[170:173], v[194:197], v[56:59]
	v_mfma_f32_16x16x32_bf16 v[44:47], v[162:165], v[206:209], v[44:47]
	v_mfma_f32_16x16x32_bf16 v[40:43], v[170:173], v[206:209], v[40:43]
	v_mfma_f32_16x16x32_bf16 v[28:31], v[162:165], v[214:217], v[28:31]
	v_mfma_f32_16x16x32_bf16 v[24:27], v[170:173], v[214:217], v[24:27]
	v_mfma_f32_16x16x32_bf16 v[12:15], v[162:165], v[222:225], v[12:15]
	v_mfma_f32_16x16x32_bf16 v[8:11], v[170:173], v[222:225], v[8:11]
	v_mfma_f32_16x16x32_bf16 v[52:55], v[174:177], v[190:193], v[52:55]
	v_mfma_f32_16x16x32_bf16 v[48:51], v[182:185], v[190:193], v[48:51]
	v_mfma_f32_16x16x32_bf16 v[36:39], v[174:177], v[198:201], v[36:39]
	v_mfma_f32_16x16x32_bf16 v[32:35], v[182:185], v[198:201], v[32:35]
	v_mfma_f32_16x16x32_bf16 v[20:23], v[174:177], v[210:213], v[20:23]
	v_mfma_f32_16x16x32_bf16 v[16:19], v[182:185], v[210:213], v[16:19]
	v_mfma_f32_16x16x32_bf16 v[4:7], v[174:177], v[218:221], v[4:7]
	v_mfma_f32_16x16x32_bf16 v[0:3], v[182:185], v[218:221], v[0:3]
	v_mfma_f32_16x16x32_bf16 v[52:55], v[178:181], v[194:197], v[52:55]
	v_mfma_f32_16x16x32_bf16 v[48:51], v[186:189], v[194:197], v[48:51]
	v_mfma_f32_16x16x32_bf16 v[36:39], v[178:181], v[206:209], v[36:39]
	v_mfma_f32_16x16x32_bf16 v[32:35], v[186:189], v[206:209], v[32:35]
	v_mfma_f32_16x16x32_bf16 v[20:23], v[178:181], v[214:217], v[20:23]
	v_mfma_f32_16x16x32_bf16 v[16:19], v[186:189], v[214:217], v[16:19]
	v_mfma_f32_16x16x32_bf16 v[4:7], v[178:181], v[222:225], v[4:7]
	v_mfma_f32_16x16x32_bf16 v[0:3], v[186:189], v[222:225], v[0:3]
	s_barrier
; #define PG8_STAGE(bufoff, gbase, voff) do { _Pragma("unroll") for (int _i = 0; _i < 2; ++_i) \
;         __builtin_amdgcn_global_load_lds((const unsigned*)((const char*)(gbase) + (voff)[_i]), (PG8_LAS unsigned*)(lds + (bufoff) + ldsw + _i * 8192), 16, 0, 0); } while (0)
; #define PG8_LDA(dst, b, h) do { _Pragma("unroll") for (int m = 0; m < 4; ++m) _Pragma("unroll") for (int k = 0; k < 2; ++k) dst[m][k] = *(const PG8_LAS bf16x8*)(lds + PG8_SA(b, h) + aoff + m * 2048 + k * 1024); } while (0)
; #define PG8_LDB(dst, b, h) do { _Pragma("unroll") for (int n = 0; n < 2; ++n) _Pragma("unroll") for (int k = 0; k < 2; ++k) dst[n][k] = *(const PG8_LAS bf16x8*)(lds + PG8_SB(b, h) + boff + n * 2048 + k * 1024); } while (0)
; #define PG8_MMA(ai, bj, At, Bt) do { __builtin_amdgcn_s_setprio(1); _Pragma("unroll") for (int m = 0; m < 4; ++m) _Pragma("unroll") for (int n = 0; n < 2; ++n) _Pragma("unroll") for (int k = 0; k < 2; ++k) \
;         acc[ai][bj][m][n] = __builtin_amdgcn_mfma_f32_16x16x32_bf16(Bt[n][k], At[m][k], acc[ai][bj][m][n], 0, 0, 0); __builtin_amdgcn_s_setprio(0); } while (0)
; #define PG8_WAIT_V(n) asm volatile("s_waitcnt vmcnt(" #n ")" ::: "memory")
; #define PG8_WAIT_L(n) asm volatile("s_waitcnt lgkmcnt(" #n ")" ::: "memory")
; #define PG8_BAR __builtin_amdgcn_s_barrier()
; #define PG8_SCHED __builtin_amdgcn_sched_barrier(0)
; template <class Epi, class Sched, bool ALIGN_EPI = false, bool SP2 = false>
; __device__ __forceinline__ void gemm_phase(PG8_LAS unsigned char* lds, const Gemm g, const Sched& S, const Epi& E) {
;     ...
;         for (int t = 0; t < nt; t += 2) {
;     ...
;             PG8_LDB(B0, 1, 0); PG8_LDB(B1, 1, 1); PG8_SCHED; PG8_LDA(At, 1, 0); PG8_STAGE(PG8_SA(0, 1), a2 + hstep, voffA);
;             PG8_WAIT_V(8); PG8_WAIT_L(0); PG8_BAR; PG8_MMA(0, 0, At, B0); PG8_MMA(0, 1, At, B1); PG8_BAR; PG8_SCHED;
;             PG8_LDA(At, 1, 1); PG8_STAGE(PG8_SB(1, 0), b3, voffB); PG8_STAGE(PG8_SB(1, 1), b3 + hstep, voffB); PG8_STAGE(PG8_SA(1, 0), a3, voffA);
;             PG8_WAIT_V(8); PG8_WAIT_L(0); PG8_BAR; PG8_MMA(1, 0, At, B0); PG8_MMA(1, 1, At, B1); PG8_BAR; PG8_SCHED;
	s_add_i32 s77, 0, 0x18000
	s_add_i32 s78, 0, 0x1c000
	ds_read_b128 v[158:161], v240
	ds_read_b128 v[162:165], v240 offset:1024
	ds_read_b128 v[166:169], v240 offset:2048
	ds_read_b128 v[170:173], v240 offset:3072
	ds_read_b128 v[174:177], v241
	ds_read_b128 v[178:181], v241 offset:1024
	ds_read_b128 v[182:185], v241 offset:2048
	ds_read_b128 v[186:189], v241 offset:3072
	s_add_u32 s100, s70, 0x80
	s_addc_u32 s101, s71, 0
	s_add_u32 s70, s70, 0x40000
	s_addc_u32 s71, s71, 0
	s_mov_b32 m0, s67
	ds_read_b128 v[190:193], v154 offset:32768
	ds_read_b128 v[194:197], v154 offset:33792
	ds_read_b128 v[198:201], v154 offset:34816
	ds_read_b128 v[206:209], v154 offset:35840
	ds_read_b128 v[210:213], v154 offset:36864
	ds_read_b128 v[214:217], v154 offset:37888
	ds_read_b128 v[218:221], v154 offset:38912
	ds_read_b128 v[222:225], v154 offset:39936
	global_load_lds_dwordx4 v130, s[70:71]
	s_mov_b32 m0, s88
	s_nop 0
	global_load_lds_dwordx4 v134, s[70:71]
	s_waitcnt vmcnt(8)
	s_waitcnt lgkmcnt(0)
	s_barrier
	v_mfma_f32_16x16x32_bf16 v[124:127], v[158:161], v[190:193], v[124:127]
	v_mfma_f32_16x16x32_bf16 v[120:123], v[166:169], v[190:193], v[120:123]
	v_mfma_f32_16x16x32_bf16 v[108:111], v[158:161], v[198:201], v[108:111]
	v_mfma_f32_16x16x32_bf16 v[104:107], v[166:169], v[198:201], v[104:107]
	v_mfma_f32_16x16x32_bf16 v[92:95], v[158:161], v[210:213], v[92:95]
	v_mfma_f32_16x16x32_bf16 v[88:91], v[166:169], v[210:213], v[88:91]
	v_mfma_f32_16x16x32_bf16 v[76:79], v[158:161], v[218:221], v[76:79]
	v_mfma_f32_16x16x32_bf16 v[72:75], v[166:169], v[218:221], v[72:75]
	v_mfma_f32_16x16x32_bf16 v[124:127], v[162:165], v[194:197], v[124:127]
	v_mfma_f32_16x16x32_bf16 v[120:123], v[170:173], v[194:197], v[120:123]
	v_mfma_f32_16x16x32_bf16 v[108:111], v[162:165], v[206:209], v[108:111]
	v_mfma_f32_16x16x32_bf16 v[104:107], v[170:173], v[206:209], v[104:107]
	v_mfma_f32_16x16x32_bf16 v[92:95], v[162:165], v[214:217], v[92:95]
	v_mfma_f32_16x16x32_bf16 v[88:91], v[170:173], v[214:217], v[88:91]
	v_mfma_f32_16x16x32_bf16 v[76:79], v[162:165], v[222:225], v[76:79]
	v_mfma_f32_16x16x32_bf16 v[72:75], v[170:173], v[222:225], v[72:75]
	v_mfma_f32_16x16x32_bf16 v[116:119], v[174:177], v[190:193], v[116:119]
	v_mfma_f32_16x16x32_bf16 v[112:115], v[182:185], v[190:193], v[112:115]
	v_mfma_f32_16x16x32_bf16 v[100:103], v[174:177], v[198:201], v[100:103]
	v_mfma_f32_16x16x32_bf16 v[96:99], v[182:185], v[198:201], v[96:99]
	v_mfma_f32_16x16x32_bf16 v[84:87], v[174:177], v[210:213], v[84:87]
	v_mfma_f32_16x16x32_bf16 v[80:83], v[182:185], v[210:213], v[80:83]
	v_mfma_f32_16x16x32_bf16 v[68:71], v[174:177], v[218:221], v[68:71]
	v_mfma_f32_16x16x32_bf16 v[64:67], v[182:185], v[218:221], v[64:67]
	v_mfma_f32_16x16x32_bf16 v[116:119], v[178:181], v[194:197], v[116:119]
	v_mfma_f32_16x16x32_bf16 v[112:115], v[186:189], v[194:197], v[112:115]
	v_mfma_f32_16x16x32_bf16 v[100:103], v[178:181], v[206:209], v[100:103]
	v_mfma_f32_16x16x32_bf16 v[96:99], v[186:189], v[206:209], v[96:99]
	v_mfma_f32_16x16x32_bf16 v[84:87], v[178:181], v[214:217], v[84:87]
	v_mfma_f32_16x16x32_bf16 v[80:83], v[186:189], v[214:217], v[80:83]
	v_mfma_f32_16x16x32_bf16 v[68:71], v[178:181], v[222:225], v[68:71]
	v_mfma_f32_16x16x32_bf16 v[64:67], v[186:189], v[222:225], v[64:67]
	s_barrier
	s_add_i32 s70, s77, s33
	s_mov_b32 m0, s70
	ds_read_b128 v[190:193], v154 offset:49152
	ds_read_b128 v[194:197], v154 offset:50176
	ds_read_b128 v[198:201], v154 offset:51200
	ds_read_b128 v[206:209], v154 offset:52224
	ds_read_b128 v[210:213], v154 offset:53248
	ds_read_b128 v[214:217], v154 offset:54272
	ds_read_b128 v[218:221], v154 offset:55296
	ds_read_b128 v[222:225], v154 offset:56320
	global_load_lds_dwordx4 v132, s[98:99]
	s_add_i32 m0, s70, 0x2000
	s_add_u32 s64, s64, 0x40080
	s_addc_u32 s65, s65, 0
	s_add_i32 s70, s78, s33
	global_load_lds_dwordx4 v136, s[98:99]
	s_mov_b32 m0, s70
	s_nop 0
	global_load_lds_dwordx4 v132, s[64:65]
	s_add_i32 m0, s70, 0x2000
	s_nop 0
	global_load_lds_dwordx4 v136, s[64:65]
	s_mov_b32 m0, s3
	s_nop 0
	global_load_lds_dwordx4 v130, s[100:101]
	s_mov_b32 m0, s68
	s_nop 0
	global_load_lds_dwordx4 v134, s[100:101]
	s_waitcnt vmcnt(8)
	s_waitcnt lgkmcnt(0)
	s_barrier
	v_mfma_f32_16x16x32_bf16 v[60:63], v[158:161], v[190:193], v[60:63]
	v_mfma_f32_16x16x32_bf16 v[56:59], v[166:169], v[190:193], v[56:59]
	v_mfma_f32_16x16x32_bf16 v[44:47], v[158:161], v[198:201], v[44:47]
	v_mfma_f32_16x16x32_bf16 v[40:43], v[166:169], v[198:201], v[40:43]
	v_mfma_f32_16x16x32_bf16 v[28:31], v[158:161], v[210:213], v[28:31]
	v_mfma_f32_16x16x32_bf16 v[24:27], v[166:169], v[210:213], v[24:27]
	v_mfma_f32_16x16x32_bf16 v[12:15], v[158:161], v[218:221], v[12:15]
	v_mfma_f32_16x16x32_bf16 v[8:11], v[166:169], v[218:221], v[8:11]
	v_mfma_f32_16x16x32_bf16 v[60:63], v[162:165], v[194:197], v[60:63]
	v_mfma_f32_16x16x32_bf16 v[56:59], v[170:173], v[194:197], v[56:59]
	v_mfma_f32_16x16x32_bf16 v[44:47], v[162:165], v[206:209], v[44:47]
	v_mfma_f32_16x16x32_bf16 v[40:43], v[170:173], v[206:209], v[40:43]
	v_mfma_f32_16x16x32_bf16 v[28:31], v[162:165], v[214:217], v[28:31]
	v_mfma_f32_16x16x32_bf16 v[24:27], v[170:173], v[214:217], v[24:27]
	v_mfma_f32_16x16x32_bf16 v[12:15], v[162:165], v[222:225], v[12:15]
	v_mfma_f32_16x16x32_bf16 v[8:11], v[170:173], v[222:225], v[8:11]
	v_mfma_f32_16x16x32_bf16 v[52:55], v[174:177], v[190:193], v[52:55]
	v_mfma_f32_16x16x32_bf16 v[48:51], v[182:185], v[190:193], v[48:51]
	v_mfma_f32_16x16x32_bf16 v[36:39], v[174:177], v[198:201], v[36:39]
	v_mfma_f32_16x16x32_bf16 v[32:35], v[182:185], v[198:201], v[32:35]
	v_mfma_f32_16x16x32_bf16 v[20:23], v[174:177], v[210:213], v[20:23]
	v_mfma_f32_16x16x32_bf16 v[16:19], v[182:185], v[210:213], v[16:19]
	v_mfma_f32_16x16x32_bf16 v[4:7], v[174:177], v[218:221], v[4:7]
	v_mfma_f32_16x16x32_bf16 v[0:3], v[182:185], v[218:221], v[0:3]
	v_mfma_f32_16x16x32_bf16 v[52:55], v[178:181], v[194:197], v[52:55]
	v_mfma_f32_16x16x32_bf16 v[48:51], v[186:189], v[194:197], v[48:51]
	v_mfma_f32_16x16x32_bf16 v[36:39], v[178:181], v[206:209], v[36:39]
	v_mfma_f32_16x16x32_bf16 v[32:35], v[186:189], v[206:209], v[32:35]
	v_mfma_f32_16x16x32_bf16 v[20:23], v[178:181], v[214:217], v[20:23]
	v_mfma_f32_16x16x32_bf16 v[16:19], v[186:189], v[214:217], v[16:19]
	v_mfma_f32_16x16x32_bf16 v[4:7], v[178:181], v[222:225], v[4:7]
	v_mfma_f32_16x16x32_bf16 v[0:3], v[186:189], v[222:225], v[0:3]
	s_barrier
	s_add_i32 s76, s76, 2
	s_add_u32 s62, s62, 0x100
	s_addc_u32 s63, s63, 0
	s_add_u32 s55, s55, 0x100
	s_addc_u32 s75, s75, 0
	s_cmp_gt_u32 s76, 13
	s_cbranch_scc0 .LBB0_136
	s_and_b64 vcc, exec, s[50:51]
	s_cbranch_vccz .LBB0_139
	s_barrier

; #define PG8_STAGE(bufoff, gbase, voff) do { _Pragma("unroll") for (int _i = 0; _i < 2; ++_i) \
;         __builtin_amdgcn_global_load_lds((const unsigned*)((const char*)(gbase) + (voff)[_i]), (PG8_LAS unsigned*)(lds + (bufoff) + ldsw + _i * 8192), 16, 0, 0); } while (0)
; #define PG8_LDA(dst, b, h) do { _Pragma("unroll") for (int m = 0; m < 4; ++m) _Pragma("unroll") for (int k = 0; k < 2; ++k) dst[m][k] = *(const PG8_LAS bf16x8*)(lds + PG8_SA(b, h) + aoff + m * 2048 + k * 1024); } while (0)
; #define PG8_LDB(dst, b, h) do { _Pragma("unroll") for (int n = 0; n < 2; ++n) _Pragma("unroll") for (int k = 0; k < 2; ++k) dst[n][k] = *(const PG8_LAS bf16x8*)(lds + PG8_SB(b, h) + boff + n * 2048 + k * 1024); } while (0)
; #define PG8_MMA(ai, bj, At, Bt) do { __builtin_amdgcn_s_setprio(1); _Pragma("unroll") for (int m = 0; m < 4; ++m) _Pragma("unroll") for (int n = 0; n < 2; ++n) _Pragma("unroll") for (int k = 0; k < 2; ++k) \
;         acc[ai][bj][m][n] = __builtin_amdgcn_mfma_f32_16x16x32_bf16(Bt[n][k], At[m][k], acc[ai][bj][m][n], 0, 0, 0); __builtin_amdgcn_s_setprio(0); } while (0)
; #define PG8_WAIT_V(n) asm volatile("s_waitcnt vmcnt(" #n ")" ::: "memory")
; #define PG8_WAIT_L(n) asm volatile("s_waitcnt lgkmcnt(" #n ")" ::: "memory")
; #define PG8_BAR __builtin_amdgcn_s_barrier()
; #define PG8_SCHED __builtin_amdgcn_sched_barrier(0)
; template <class Epi, class Sched, bool ALIGN_EPI = false, bool SP2 = false>
; __device__ __forceinline__ void gemm_phase(PG8_LAS unsigned char* lds, const Gemm g, const Sched& S, const Epi& E) {
;     ...
;             PG8_LDB(B0, 0, 0); PG8_LDB(B1, 0, 1); PG8_SCHED; PG8_LDA(At, 0, 0); PG8_STAGE(PG8_SA(1, 1), a1 + hstep, voffA);
;             PG8_WAIT_V(8); PG8_WAIT_L(0); PG8_BAR; PG8_MMA(0, 0, At, B0); PG8_MMA(0, 1, At, B1); PG8_BAR; PG8_SCHED;
;             PG8_LDA(At, 0, 1); PG8_STAGE(PG8_SB(0, 0), b2, voffB); PG8_STAGE(PG8_SB(0, 1), b2 + hstep, voffB); PG8_STAGE(PG8_SA(0, 0), a2, voffA);
;             PG8_WAIT_V(8); PG8_WAIT_L(0); PG8_BAR; PG8_MMA(1, 0, At, B0); PG8_MMA(1, 1, At, B1); PG8_BAR; PG8_SCHED;
.LBB0_520:
	ds_read_b128 v[146:149], v152
	ds_read_b128 v[156:159], v152 offset:1024
	ds_read_b128 v[160:163], v152 offset:2048
	ds_read_b128 v[164:167], v152 offset:3072
	ds_read_b128 v[168:171], v153
	ds_read_b128 v[172:175], v153 offset:1024
	ds_read_b128 v[176:179], v153 offset:2048
	ds_read_b128 v[180:183], v153 offset:3072
	s_add_u32 s46, s44, 0xfffc0080
	s_addc_u32 s47, s45, -1
	s_cmp_eq_u32 s63, 12
	s_cselect_b32 s49, s35, s47
	s_cselect_b32 s48, s41, s46
	s_cselect_b32 s47, s31, s62
	s_cselect_b32 s46, s60, s61
	s_add_i32 m0, s43, 0xc000
	ds_read_b128 v[184:187], v154
	ds_read_b128 v[188:191], v154 offset:1024
	ds_read_b128 v[192:195], v154 offset:2048
	ds_read_b128 v[196:199], v154 offset:3072
	ds_read_b128 v[200:203], v154 offset:4096
	ds_read_b128 v[206:209], v154 offset:5120
	ds_read_b128 v[210:213], v154 offset:6144
	ds_read_b128 v[214:217], v154 offset:7168
	global_load_lds_dwordx4 v138, s[44:45]
	s_add_i32 m0, s43, 0xe000
	s_nop 0
	global_load_lds_dwordx4 v140, s[44:45]
	s_waitcnt vmcnt(8)
	s_waitcnt lgkmcnt(0)
	s_barrier
	v_mfma_f32_16x16x32_bf16 v[124:127], v[146:149], v[184:187], v[124:127]
	v_mfma_f32_16x16x32_bf16 v[120:123], v[160:163], v[184:187], v[120:123]
	v_mfma_f32_16x16x32_bf16 v[108:111], v[146:149], v[192:195], v[108:111]
	v_mfma_f32_16x16x32_bf16 v[104:107], v[160:163], v[192:195], v[104:107]
	v_mfma_f32_16x16x32_bf16 v[92:95], v[146:149], v[200:203], v[92:95]
	v_mfma_f32_16x16x32_bf16 v[88:91], v[160:163], v[200:203], v[88:91]
	v_mfma_f32_16x16x32_bf16 v[76:79], v[146:149], v[210:213], v[76:79]
	v_mfma_f32_16x16x32_bf16 v[72:75], v[160:163], v[210:213], v[72:75]
	v_mfma_f32_16x16x32_bf16 v[124:127], v[156:159], v[188:191], v[124:127]
	v_mfma_f32_16x16x32_bf16 v[120:123], v[164:167], v[188:191], v[120:123]
	v_mfma_f32_16x16x32_bf16 v[108:111], v[156:159], v[196:199], v[108:111]
	v_mfma_f32_16x16x32_bf16 v[104:107], v[164:167], v[196:199], v[104:107]
	v_mfma_f32_16x16x32_bf16 v[92:95], v[156:159], v[206:209], v[92:95]
	v_mfma_f32_16x16x32_bf16 v[88:91], v[164:167], v[206:209], v[88:91]
	v_mfma_f32_16x16x32_bf16 v[76:79], v[156:159], v[214:217], v[76:79]
	v_mfma_f32_16x16x32_bf16 v[72:75], v[164:167], v[214:217], v[72:75]
	v_mfma_f32_16x16x32_bf16 v[116:119], v[168:171], v[184:187], v[116:119]
	v_mfma_f32_16x16x32_bf16 v[112:115], v[176:179], v[184:187], v[112:115]
	v_mfma_f32_16x16x32_bf16 v[100:103], v[168:171], v[192:195], v[100:103]
	v_mfma_f32_16x16x32_bf16 v[96:99], v[176:179], v[192:195], v[96:99]
	v_mfma_f32_16x16x32_bf16 v[84:87], v[168:171], v[200:203], v[84:87]
	v_mfma_f32_16x16x32_bf16 v[80:83], v[176:179], v[200:203], v[80:83]
	v_mfma_f32_16x16x32_bf16 v[68:71], v[168:171], v[210:213], v[68:71]
	v_mfma_f32_16x16x32_bf16 v[64:67], v[176:179], v[210:213], v[64:67]
	v_mfma_f32_16x16x32_bf16 v[116:119], v[172:175], v[188:191], v[116:119]
	v_mfma_f32_16x16x32_bf16 v[112:115], v[180:183], v[188:191], v[112:115]
	v_mfma_f32_16x16x32_bf16 v[100:103], v[172:175], v[196:199], v[100:103]
	v_mfma_f32_16x16x32_bf16 v[96:99], v[180:183], v[196:199], v[96:99]
	v_mfma_f32_16x16x32_bf16 v[84:87], v[172:175], v[206:209], v[84:87]
	v_mfma_f32_16x16x32_bf16 v[80:83], v[180:183], v[206:209], v[80:83]
	v_mfma_f32_16x16x32_bf16 v[68:71], v[172:175], v[214:217], v[68:71]
	v_mfma_f32_16x16x32_bf16 v[64:67], v[180:183], v[214:217], v[64:67]
	s_barrier
	s_add_i32 s64, s58, s13
	s_mov_b32 m0, s64
	ds_read_b128 v[184:187], v154 offset:16384
	ds_read_b128 v[188:191], v154 offset:17408
	ds_read_b128 v[192:195], v154 offset:18432
	ds_read_b128 v[196:199], v154 offset:19456
	ds_read_b128 v[200:203], v154 offset:20480
	ds_read_b128 v[206:209], v154 offset:21504
	ds_read_b128 v[210:213], v154 offset:22528
	ds_read_b128 v[214:217], v154 offset:23552
	global_load_lds_dwordx4 v132, s[46:47]
	s_add_i32 m0, s64, 0x2000
	s_add_u32 s98, s46, 0x80
	s_addc_u32 s99, s47, 0
	s_add_u32 s64, s46, 0x40000
	s_addc_u32 s65, s47, 0
	s_add_i32 s66, s59, s13
	global_load_lds_dwordx4 v136, s[46:47]
	s_mov_b32 m0, s66
	s_nop 0
	global_load_lds_dwordx4 v132, s[64:65]
	s_add_i32 m0, s66, 0x2000
	s_nop 0
	global_load_lds_dwordx4 v136, s[64:65]
	s_mov_b32 m0, s43
	s_nop 0
	global_load_lds_dwordx4 v130, s[48:49]
	s_mov_b32 m0, s50
	s_nop 0
	global_load_lds_dwordx4 v134, s[48:49]
	s_waitcnt vmcnt(8)
	s_waitcnt lgkmcnt(0)
	s_barrier
	v_mfma_f32_16x16x32_bf16 v[60:63], v[146:149], v[184:187], v[60:63]
	v_mfma_f32_16x16x32_bf16 v[56:59], v[160:163], v[184:187], v[56:59]
	v_mfma_f32_16x16x32_bf16 v[44:47], v[146:149], v[192:195], v[44:47]
	v_mfma_f32_16x16x32_bf16 v[40:43], v[160:163], v[192:195], v[40:43]
	v_mfma_f32_16x16x32_bf16 v[28:31], v[146:149], v[200:203], v[28:31]
	v_mfma_f32_16x16x32_bf16 v[24:27], v[160:163], v[200:203], v[24:27]
	v_mfma_f32_16x16x32_bf16 v[12:15], v[146:149], v[210:213], v[12:15]
	v_mfma_f32_16x16x32_bf16 v[8:11], v[160:163], v[210:213], v[8:11]
	v_mfma_f32_16x16x32_bf16 v[60:63], v[156:159], v[188:191], v[60:63]
	v_mfma_f32_16x16x32_bf16 v[56:59], v[164:167], v[188:191], v[56:59]
	v_mfma_f32_16x16x32_bf16 v[44:47], v[156:159], v[196:199], v[44:47]
	v_mfma_f32_16x16x32_bf16 v[40:43], v[164:167], v[196:199], v[40:43]
	v_mfma_f32_16x16x32_bf16 v[28:31], v[156:159], v[206:209], v[28:31]
	v_mfma_f32_16x16x32_bf16 v[24:27], v[164:167], v[206:209], v[24:27]
	v_mfma_f32_16x16x32_bf16 v[12:15], v[156:159], v[214:217], v[12:15]
	v_mfma_f32_16x16x32_bf16 v[8:11], v[164:167], v[214:217], v[8:11]
	v_mfma_f32_16x16x32_bf16 v[52:55], v[168:171], v[184:187], v[52:55]
	v_mfma_f32_16x16x32_bf16 v[48:51], v[176:179], v[184:187], v[48:51]
	v_mfma_f32_16x16x32_bf16 v[36:39], v[168:171], v[192:195], v[36:39]
	v_mfma_f32_16x16x32_bf16 v[32:35], v[176:179], v[192:195], v[32:35]
	v_mfma_f32_16x16x32_bf16 v[20:23], v[168:171], v[200:203], v[20:23]
	v_mfma_f32_16x16x32_bf16 v[16:19], v[176:179], v[200:203], v[16:19]
	v_mfma_f32_16x16x32_bf16 v[4:7], v[168:171], v[210:213], v[4:7]
	v_mfma_f32_16x16x32_bf16 v[0:3], v[176:179], v[210:213], v[0:3]
	v_mfma_f32_16x16x32_bf16 v[52:55], v[172:175], v[188:191], v[52:55]
	v_mfma_f32_16x16x32_bf16 v[48:51], v[180:183], v[188:191], v[48:51]
	v_mfma_f32_16x16x32_bf16 v[36:39], v[172:175], v[196:199], v[36:39]
	v_mfma_f32_16x16x32_bf16 v[32:35], v[180:183], v[196:199], v[32:35]
	v_mfma_f32_16x16x32_bf16 v[20:23], v[172:175], v[206:209], v[20:23]
	v_mfma_f32_16x16x32_bf16 v[16:19], v[180:183], v[206:209], v[16:19]
	v_mfma_f32_16x16x32_bf16 v[4:7], v[172:175], v[214:217], v[4:7]
	v_mfma_f32_16x16x32_bf16 v[0:3], v[180:183], v[214:217], v[0:3]
	s_barrier
; #define PG8_STAGE(bufoff, gbase, voff) do { _Pragma("unroll") for (int _i = 0; _i < 2; ++_i) \
;         __builtin_amdgcn_global_load_lds((const unsigned*)((const char*)(gbase) + (voff)[_i]), (PG8_LAS unsigned*)(lds + (bufoff) + ldsw + _i * 8192), 16, 0, 0); } while (0)
; #define PG8_LDA(dst, b, h) do { _Pragma("unroll") for (int m = 0; m < 4; ++m) _Pragma("unroll") for (int k = 0; k < 2; ++k) dst[m][k] = *(const PG8_LAS bf16x8*)(lds + PG8_SA(b, h) + aoff + m * 2048 + k * 1024); } while (0)
; #define PG8_LDB(dst, b, h) do { _Pragma("unroll") for (int n = 0; n < 2; ++n) _Pragma("unroll") for (int k = 0; k < 2; ++k) dst[n][k] = *(const PG8_LAS bf16x8*)(lds + PG8_SB(b, h) + boff + n * 2048 + k * 1024); } while (0)
; #define PG8_MMA(ai, bj, At, Bt) do { __builtin_amdgcn_s_setprio(1); _Pragma("unroll") for (int m = 0; m < 4; ++m) _Pragma("unroll") for (int n = 0; n < 2; ++n) _Pragma("unroll") for (int k = 0; k < 2; ++k) \
;         acc[ai][bj][m][n] = __builtin_amdgcn_mfma_f32_16x16x32_bf16(Bt[n][k], At[m][k], acc[ai][bj][m][n], 0, 0, 0); __builtin_amdgcn_s_setprio(0); } while (0)
; #define PG8_WAIT_V(n) asm volatile("s_waitcnt vmcnt(" #n ")" ::: "memory")
; #define PG8_WAIT_L(n) asm volatile("s_waitcnt lgkmcnt(" #n ")" ::: "memory")
; #define PG8_BAR __builtin_amdgcn_s_barrier()
; #define PG8_SCHED __builtin_amdgcn_sched_barrier(0)
; template <class Epi, class Sched, bool ALIGN_EPI = false, bool SP2 = false>
; __device__ __forceinline__ void gemm_phase(PG8_LAS unsigned char* lds, const Gemm g, const Sched& S, const Epi& E) {
;     ...
;         for (int t = 0; t < nt; t += 2) {
;     ...
;             PG8_LDB(B0, 1, 0); PG8_LDB(B1, 1, 1); PG8_SCHED; PG8_LDA(At, 1, 0); PG8_STAGE(PG8_SA(0, 1), a2 + hstep, voffA);
;             PG8_WAIT_V(8); PG8_WAIT_L(0); PG8_BAR; PG8_MMA(0, 0, At, B0); PG8_MMA(0, 1, At, B1); PG8_BAR; PG8_SCHED;
;             PG8_LDA(At, 1, 1); PG8_STAGE(PG8_SB(1, 0), b3, voffB); PG8_STAGE(PG8_SB(1, 1), b3 + hstep, voffB); PG8_STAGE(PG8_SA(1, 0), a3, voffA);
;             PG8_WAIT_V(8); PG8_WAIT_L(0); PG8_BAR; PG8_MMA(1, 0, At, B0); PG8_MMA(1, 1, At, B1); PG8_BAR; PG8_SCHED;
	s_add_i32 s64, 0, 0x18000
	s_add_i32 s65, 0, 0x1c000
	ds_read_b128 v[146:149], v240
	ds_read_b128 v[156:159], v240 offset:1024
	ds_read_b128 v[160:163], v240 offset:2048
	ds_read_b128 v[164:167], v240 offset:3072
	ds_read_b128 v[168:171], v241
	ds_read_b128 v[172:175], v241 offset:1024
	ds_read_b128 v[176:179], v241 offset:2048
	ds_read_b128 v[180:183], v241 offset:3072
	s_add_u32 s100, s48, 0x80
	s_addc_u32 s101, s49, 0
	s_add_u32 s48, s48, 0x40000
	s_addc_u32 s49, s49, 0
	s_mov_b32 m0, s51
	ds_read_b128 v[184:187], v154 offset:32768
	ds_read_b128 v[188:191], v154 offset:33792
	ds_read_b128 v[192:195], v154 offset:34816
	ds_read_b128 v[196:199], v154 offset:35840
	ds_read_b128 v[200:203], v154 offset:36864
	ds_read_b128 v[206:209], v154 offset:37888
	ds_read_b128 v[210:213], v154 offset:38912
	ds_read_b128 v[214:217], v154 offset:39936
	global_load_lds_dwordx4 v130, s[48:49]
	s_mov_b32 m0, s52
	s_nop 0
	global_load_lds_dwordx4 v134, s[48:49]
	s_waitcnt vmcnt(8)
	s_waitcnt lgkmcnt(0)
	s_barrier
	v_mfma_f32_16x16x32_bf16 v[124:127], v[146:149], v[184:187], v[124:127]
	v_mfma_f32_16x16x32_bf16 v[120:123], v[160:163], v[184:187], v[120:123]
	v_mfma_f32_16x16x32_bf16 v[108:111], v[146:149], v[192:195], v[108:111]
	v_mfma_f32_16x16x32_bf16 v[104:107], v[160:163], v[192:195], v[104:107]
	v_mfma_f32_16x16x32_bf16 v[92:95], v[146:149], v[200:203], v[92:95]
	v_mfma_f32_16x16x32_bf16 v[88:91], v[160:163], v[200:203], v[88:91]
	v_mfma_f32_16x16x32_bf16 v[76:79], v[146:149], v[210:213], v[76:79]
	v_mfma_f32_16x16x32_bf16 v[72:75], v[160:163], v[210:213], v[72:75]
	v_mfma_f32_16x16x32_bf16 v[124:127], v[156:159], v[188:191], v[124:127]
	v_mfma_f32_16x16x32_bf16 v[120:123], v[164:167], v[188:191], v[120:123]
	v_mfma_f32_16x16x32_bf16 v[108:111], v[156:159], v[196:199], v[108:111]
	v_mfma_f32_16x16x32_bf16 v[104:107], v[164:167], v[196:199], v[104:107]
	v_mfma_f32_16x16x32_bf16 v[92:95], v[156:159], v[206:209], v[92:95]
	v_mfma_f32_16x16x32_bf16 v[88:91], v[164:167], v[206:209], v[88:91]
	v_mfma_f32_16x16x32_bf16 v[76:79], v[156:159], v[214:217], v[76:79]
	v_mfma_f32_16x16x32_bf16 v[72:75], v[164:167], v[214:217], v[72:75]
	v_mfma_f32_16x16x32_bf16 v[116:119], v[168:171], v[184:187], v[116:119]
	v_mfma_f32_16x16x32_bf16 v[112:115], v[176:179], v[184:187], v[112:115]
	v_mfma_f32_16x16x32_bf16 v[100:103], v[168:171], v[192:195], v[100:103]
	v_mfma_f32_16x16x32_bf16 v[96:99], v[176:179], v[192:195], v[96:99]
	v_mfma_f32_16x16x32_bf16 v[84:87], v[168:171], v[200:203], v[84:87]
	v_mfma_f32_16x16x32_bf16 v[80:83], v[176:179], v[200:203], v[80:83]
	v_mfma_f32_16x16x32_bf16 v[68:71], v[168:171], v[210:213], v[68:71]
	v_mfma_f32_16x16x32_bf16 v[64:67], v[176:179], v[210:213], v[64:67]
	v_mfma_f32_16x16x32_bf16 v[116:119], v[172:175], v[188:191], v[116:119]
	v_mfma_f32_16x16x32_bf16 v[112:115], v[180:183], v[188:191], v[112:115]
	v_mfma_f32_16x16x32_bf16 v[100:103], v[172:175], v[196:199], v[100:103]
	v_mfma_f32_16x16x32_bf16 v[96:99], v[180:183], v[196:199], v[96:99]
	v_mfma_f32_16x16x32_bf16 v[84:87], v[172:175], v[206:209], v[84:87]
	v_mfma_f32_16x16x32_bf16 v[80:83], v[180:183], v[206:209], v[80:83]
	v_mfma_f32_16x16x32_bf16 v[68:71], v[172:175], v[214:217], v[68:71]
	v_mfma_f32_16x16x32_bf16 v[64:67], v[180:183], v[214:217], v[64:67]
	s_barrier
	s_add_i32 s48, s64, s13
	s_mov_b32 m0, s48
	ds_read_b128 v[184:187], v154 offset:49152
	ds_read_b128 v[188:191], v154 offset:50176
	ds_read_b128 v[192:195], v154 offset:51200
	ds_read_b128 v[196:199], v154 offset:52224
	ds_read_b128 v[200:203], v154 offset:53248
	ds_read_b128 v[206:209], v154 offset:54272
	ds_read_b128 v[210:213], v154 offset:55296
	ds_read_b128 v[214:217], v154 offset:56320
	global_load_lds_dwordx4 v132, s[98:99]
	s_add_i32 m0, s48, 0x2000
	s_add_u32 s46, s46, 0x40080
	s_addc_u32 s47, s47, 0
	s_add_i32 s48, s65, s13
	global_load_lds_dwordx4 v136, s[98:99]
	s_mov_b32 m0, s48
	s_nop 0
	global_load_lds_dwordx4 v132, s[46:47]
	s_add_i32 m0, s48, 0x2000
	s_nop 0
	global_load_lds_dwordx4 v136, s[46:47]
	s_mov_b32 m0, s54
	s_nop 0
	global_load_lds_dwordx4 v130, s[100:101]
	s_mov_b32 m0, s55
	s_nop 0
	global_load_lds_dwordx4 v134, s[100:101]
	s_waitcnt vmcnt(8)
	s_waitcnt lgkmcnt(0)
	s_barrier
	v_mfma_f32_16x16x32_bf16 v[60:63], v[146:149], v[184:187], v[60:63]
	v_mfma_f32_16x16x32_bf16 v[56:59], v[160:163], v[184:187], v[56:59]
	v_mfma_f32_16x16x32_bf16 v[44:47], v[146:149], v[192:195], v[44:47]
	v_mfma_f32_16x16x32_bf16 v[40:43], v[160:163], v[192:195], v[40:43]
	v_mfma_f32_16x16x32_bf16 v[28:31], v[146:149], v[200:203], v[28:31]
	v_mfma_f32_16x16x32_bf16 v[24:27], v[160:163], v[200:203], v[24:27]
	v_mfma_f32_16x16x32_bf16 v[12:15], v[146:149], v[210:213], v[12:15]
	v_mfma_f32_16x16x32_bf16 v[8:11], v[160:163], v[210:213], v[8:11]
	v_mfma_f32_16x16x32_bf16 v[60:63], v[156:159], v[188:191], v[60:63]
	v_mfma_f32_16x16x32_bf16 v[56:59], v[164:167], v[188:191], v[56:59]
	v_mfma_f32_16x16x32_bf16 v[44:47], v[156:159], v[196:199], v[44:47]
	v_mfma_f32_16x16x32_bf16 v[40:43], v[164:167], v[196:199], v[40:43]
	v_mfma_f32_16x16x32_bf16 v[28:31], v[156:159], v[206:209], v[28:31]
	v_mfma_f32_16x16x32_bf16 v[24:27], v[164:167], v[206:209], v[24:27]
	v_mfma_f32_16x16x32_bf16 v[12:15], v[156:159], v[214:217], v[12:15]
	v_mfma_f32_16x16x32_bf16 v[8:11], v[164:167], v[214:217], v[8:11]
	v_mfma_f32_16x16x32_bf16 v[52:55], v[168:171], v[184:187], v[52:55]
	v_mfma_f32_16x16x32_bf16 v[48:51], v[176:179], v[184:187], v[48:51]
	v_mfma_f32_16x16x32_bf16 v[36:39], v[168:171], v[192:195], v[36:39]
	v_mfma_f32_16x16x32_bf16 v[32:35], v[176:179], v[192:195], v[32:35]
	v_mfma_f32_16x16x32_bf16 v[20:23], v[168:171], v[200:203], v[20:23]
	v_mfma_f32_16x16x32_bf16 v[16:19], v[176:179], v[200:203], v[16:19]
	v_mfma_f32_16x16x32_bf16 v[4:7], v[168:171], v[210:213], v[4:7]
	v_mfma_f32_16x16x32_bf16 v[0:3], v[176:179], v[210:213], v[0:3]
	v_mfma_f32_16x16x32_bf16 v[52:55], v[172:175], v[188:191], v[52:55]
	v_mfma_f32_16x16x32_bf16 v[48:51], v[180:183], v[188:191], v[48:51]
	v_mfma_f32_16x16x32_bf16 v[36:39], v[172:175], v[196:199], v[36:39]
	v_mfma_f32_16x16x32_bf16 v[32:35], v[180:183], v[196:199], v[32:35]
	v_mfma_f32_16x16x32_bf16 v[20:23], v[172:175], v[206:209], v[20:23]
	v_mfma_f32_16x16x32_bf16 v[16:19], v[180:183], v[206:209], v[16:19]
	v_mfma_f32_16x16x32_bf16 v[4:7], v[172:175], v[214:217], v[4:7]
	v_mfma_f32_16x16x32_bf16 v[0:3], v[180:183], v[214:217], v[0:3]
	s_barrier
	s_add_i32 s63, s63, 2
	s_add_u32 s44, s44, 0x100
	s_addc_u32 s45, s45, 0
	s_add_u32 s61, s61, 0x100
	s_addc_u32 s62, s62, 0
	s_cmp_gt_u32 s63, 13
	s_cbranch_scc0 .LBB0_520
	s_and_b64 vcc, exec, s[28:29]
	s_cbranch_vccz .LBB0_523
	s_barrier

; #define PG8_STAGE(bufoff, gbase, voff) do { _Pragma("unroll") for (int _i = 0; _i < 2; ++_i) \
;         __builtin_amdgcn_global_load_lds((const unsigned*)((const char*)(gbase) + (voff)[_i]), (PG8_LAS unsigned*)(lds + (bufoff) + ldsw + _i * 8192), 16, 0, 0); } while (0)
; #define PG8_LDA(dst, b, h) do { _Pragma("unroll") for (int m = 0; m < 4; ++m) _Pragma("unroll") for (int k = 0; k < 2; ++k) dst[m][k] = *(const PG8_LAS bf16x8*)(lds + PG8_SA(b, h) + aoff + m * 2048 + k * 1024); } while (0)
; #define PG8_LDB(dst, b, h) do { _Pragma("unroll") for (int n = 0; n < 2; ++n) _Pragma("unroll") for (int k = 0; k < 2; ++k) dst[n][k] = *(const PG8_LAS bf16x8*)(lds + PG8_SB(b, h) + boff + n * 2048 + k * 1024); } while (0)
; #define PG8_MMA(ai, bj, At, Bt) do { __builtin_amdgcn_s_setprio(1); _Pragma("unroll") for (int m = 0; m < 4; ++m) _Pragma("unroll") for (int n = 0; n < 2; ++n) _Pragma("unroll") for (int k = 0; k < 2; ++k) \
;         acc[ai][bj][m][n] = __builtin_amdgcn_mfma_f32_16x16x32_bf16(Bt[n][k], At[m][k], acc[ai][bj][m][n], 0, 0, 0); __builtin_amdgcn_s_setprio(0); } while (0)
; #define PG8_WAIT_V(n) asm volatile("s_waitcnt vmcnt(" #n ")" ::: "memory")
; #define PG8_WAIT_L(n) asm volatile("s_waitcnt lgkmcnt(" #n ")" ::: "memory")
; #define PG8_BAR __builtin_amdgcn_s_barrier()
; #define PG8_SCHED __builtin_amdgcn_sched_barrier(0)
; template <class Epi, class Sched, bool ALIGN_EPI = false, bool SP2 = false>
; __device__ __forceinline__ void gemm_phase(PG8_LAS unsigned char* lds, const Gemm g, const Sched& S, const Epi& E) {
;     ...
;             PG8_LDB(B0, 0, 0); PG8_LDB(B1, 0, 1); PG8_SCHED; PG8_LDA(At, 0, 0); PG8_STAGE(PG8_SA(1, 1), a1 + hstep, voffA);
;             PG8_WAIT_V(8); PG8_WAIT_L(0); PG8_BAR; PG8_MMA(0, 0, At, B0); PG8_MMA(0, 1, At, B1); PG8_BAR; PG8_SCHED;
;             PG8_LDA(At, 0, 1); PG8_STAGE(PG8_SB(0, 0), b2, voffB); PG8_STAGE(PG8_SB(0, 1), b2 + hstep, voffB); PG8_STAGE(PG8_SA(0, 0), a2, voffA);
;             PG8_WAIT_V(8); PG8_WAIT_L(0); PG8_BAR; PG8_MMA(1, 0, At, B0); PG8_MMA(1, 1, At, B1); PG8_BAR; PG8_SCHED;
.LBB0_627:
	ds_read_b128 v[154:157], v149
	ds_read_b128 v[158:161], v149 offset:1024
	ds_read_b128 v[162:165], v149 offset:2048
	ds_read_b128 v[166:169], v149 offset:3072
	ds_read_b128 v[170:173], v150
	ds_read_b128 v[174:177], v150 offset:1024
	ds_read_b128 v[178:181], v150 offset:2048
	ds_read_b128 v[182:185], v150 offset:3072
	s_add_u32 s44, s42, 0xfffc0080
	s_addc_u32 s45, s43, -1
	s_cmp_eq_u32 s64, 12
	s_cselect_b32 s47, s37, s45
	s_cselect_b32 s46, s60, s44
	s_cselect_b32 s45, s35, s63
	s_cselect_b32 s44, s61, s62
	s_add_i32 m0, s48, 0xc000
	ds_read_b128 v[186:189], v151
	ds_read_b128 v[190:193], v151 offset:1024
	ds_read_b128 v[194:197], v151 offset:2048
	ds_read_b128 v[198:201], v151 offset:3072
	ds_read_b128 v[206:209], v151 offset:4096
	ds_read_b128 v[210:213], v151 offset:5120
	ds_read_b128 v[214:217], v151 offset:6144
	ds_read_b128 v[218:221], v151 offset:7168
	global_load_lds_dwordx4 v138, s[42:43]
	s_add_i32 m0, s48, 0xe000
	s_nop 0
	global_load_lds_dwordx4 v140, s[42:43]
	s_waitcnt vmcnt(8)
	s_waitcnt lgkmcnt(0)
	s_barrier
	v_mfma_f32_16x16x32_bf16 v[124:127], v[154:157], v[186:189], v[124:127]
	v_mfma_f32_16x16x32_bf16 v[120:123], v[162:165], v[186:189], v[120:123]
	v_mfma_f32_16x16x32_bf16 v[108:111], v[154:157], v[194:197], v[108:111]
	v_mfma_f32_16x16x32_bf16 v[104:107], v[162:165], v[194:197], v[104:107]
	v_mfma_f32_16x16x32_bf16 v[92:95], v[154:157], v[206:209], v[92:95]
	v_mfma_f32_16x16x32_bf16 v[88:91], v[162:165], v[206:209], v[88:91]
	v_mfma_f32_16x16x32_bf16 v[76:79], v[154:157], v[214:217], v[76:79]
	v_mfma_f32_16x16x32_bf16 v[72:75], v[162:165], v[214:217], v[72:75]
	v_mfma_f32_16x16x32_bf16 v[124:127], v[158:161], v[190:193], v[124:127]
	v_mfma_f32_16x16x32_bf16 v[120:123], v[166:169], v[190:193], v[120:123]
	v_mfma_f32_16x16x32_bf16 v[108:111], v[158:161], v[198:201], v[108:111]
	v_mfma_f32_16x16x32_bf16 v[104:107], v[166:169], v[198:201], v[104:107]
	v_mfma_f32_16x16x32_bf16 v[92:95], v[158:161], v[210:213], v[92:95]
	v_mfma_f32_16x16x32_bf16 v[88:91], v[166:169], v[210:213], v[88:91]
	v_mfma_f32_16x16x32_bf16 v[76:79], v[158:161], v[218:221], v[76:79]
	v_mfma_f32_16x16x32_bf16 v[72:75], v[166:169], v[218:221], v[72:75]
	v_mfma_f32_16x16x32_bf16 v[116:119], v[170:173], v[186:189], v[116:119]
	v_mfma_f32_16x16x32_bf16 v[112:115], v[178:181], v[186:189], v[112:115]
	v_mfma_f32_16x16x32_bf16 v[100:103], v[170:173], v[194:197], v[100:103]
	v_mfma_f32_16x16x32_bf16 v[96:99], v[178:181], v[194:197], v[96:99]
	v_mfma_f32_16x16x32_bf16 v[84:87], v[170:173], v[206:209], v[84:87]
	v_mfma_f32_16x16x32_bf16 v[80:83], v[178:181], v[206:209], v[80:83]
	v_mfma_f32_16x16x32_bf16 v[68:71], v[170:173], v[214:217], v[68:71]
	v_mfma_f32_16x16x32_bf16 v[64:67], v[178:181], v[214:217], v[64:67]
	v_mfma_f32_16x16x32_bf16 v[116:119], v[174:177], v[190:193], v[116:119]
	v_mfma_f32_16x16x32_bf16 v[112:115], v[182:185], v[190:193], v[112:115]
	v_mfma_f32_16x16x32_bf16 v[100:103], v[174:177], v[198:201], v[100:103]
	v_mfma_f32_16x16x32_bf16 v[96:99], v[182:185], v[198:201], v[96:99]
	v_mfma_f32_16x16x32_bf16 v[84:87], v[174:177], v[210:213], v[84:87]
	v_mfma_f32_16x16x32_bf16 v[80:83], v[182:185], v[210:213], v[80:83]
	v_mfma_f32_16x16x32_bf16 v[68:71], v[174:177], v[218:221], v[68:71]
	v_mfma_f32_16x16x32_bf16 v[64:67], v[182:185], v[218:221], v[64:67]
	s_barrier
	s_add_i32 s65, s57, s13
	s_mov_b32 m0, s65
	ds_read_b128 v[186:189], v151 offset:16384
	ds_read_b128 v[190:193], v151 offset:17408
	ds_read_b128 v[194:197], v151 offset:18432
	ds_read_b128 v[198:201], v151 offset:19456
	ds_read_b128 v[206:209], v151 offset:20480
	ds_read_b128 v[210:213], v151 offset:21504
	ds_read_b128 v[214:217], v151 offset:22528
	ds_read_b128 v[218:221], v151 offset:23552
	global_load_lds_dwordx4 v132, s[44:45]
	s_add_i32 m0, s65, 0x2000
	s_add_u32 s98, s44, 0x80
	s_addc_u32 s99, s45, 0
	s_add_u32 s66, s44, 0x40000
	s_addc_u32 s67, s45, 0
	s_add_i32 s65, s58, s13
	global_load_lds_dwordx4 v136, s[44:45]
	s_mov_b32 m0, s65
	s_nop 0
	global_load_lds_dwordx4 v132, s[66:67]
	s_add_i32 m0, s65, 0x2000
	s_nop 0
	global_load_lds_dwordx4 v136, s[66:67]
	s_mov_b32 m0, s48
	s_nop 0
	global_load_lds_dwordx4 v130, s[46:47]
	s_mov_b32 m0, s49
	s_nop 0
	global_load_lds_dwordx4 v134, s[46:47]
	s_waitcnt vmcnt(8)
	s_waitcnt lgkmcnt(0)
	s_barrier
	v_mfma_f32_16x16x32_bf16 v[60:63], v[154:157], v[186:189], v[60:63]
	v_mfma_f32_16x16x32_bf16 v[56:59], v[162:165], v[186:189], v[56:59]
	v_mfma_f32_16x16x32_bf16 v[44:47], v[154:157], v[194:197], v[44:47]
	v_mfma_f32_16x16x32_bf16 v[40:43], v[162:165], v[194:197], v[40:43]
	v_mfma_f32_16x16x32_bf16 v[28:31], v[154:157], v[206:209], v[28:31]
	v_mfma_f32_16x16x32_bf16 v[24:27], v[162:165], v[206:209], v[24:27]
	v_mfma_f32_16x16x32_bf16 v[12:15], v[154:157], v[214:217], v[12:15]
	v_mfma_f32_16x16x32_bf16 v[8:11], v[162:165], v[214:217], v[8:11]
	v_mfma_f32_16x16x32_bf16 v[60:63], v[158:161], v[190:193], v[60:63]
	v_mfma_f32_16x16x32_bf16 v[56:59], v[166:169], v[190:193], v[56:59]
	v_mfma_f32_16x16x32_bf16 v[44:47], v[158:161], v[198:201], v[44:47]
	v_mfma_f32_16x16x32_bf16 v[40:43], v[166:169], v[198:201], v[40:43]
	v_mfma_f32_16x16x32_bf16 v[28:31], v[158:161], v[210:213], v[28:31]
	v_mfma_f32_16x16x32_bf16 v[24:27], v[166:169], v[210:213], v[24:27]
	v_mfma_f32_16x16x32_bf16 v[12:15], v[158:161], v[218:221], v[12:15]
	v_mfma_f32_16x16x32_bf16 v[8:11], v[166:169], v[218:221], v[8:11]
	v_mfma_f32_16x16x32_bf16 v[52:55], v[170:173], v[186:189], v[52:55]
	v_mfma_f32_16x16x32_bf16 v[48:51], v[178:181], v[186:189], v[48:51]
	v_mfma_f32_16x16x32_bf16 v[36:39], v[170:173], v[194:197], v[36:39]
	v_mfma_f32_16x16x32_bf16 v[32:35], v[178:181], v[194:197], v[32:35]
	v_mfma_f32_16x16x32_bf16 v[20:23], v[170:173], v[206:209], v[20:23]
	v_mfma_f32_16x16x32_bf16 v[16:19], v[178:181], v[206:209], v[16:19]
	v_mfma_f32_16x16x32_bf16 v[4:7], v[170:173], v[214:217], v[4:7]
	v_mfma_f32_16x16x32_bf16 v[0:3], v[178:181], v[214:217], v[0:3]
	v_mfma_f32_16x16x32_bf16 v[52:55], v[174:177], v[190:193], v[52:55]
	v_mfma_f32_16x16x32_bf16 v[48:51], v[182:185], v[190:193], v[48:51]
	v_mfma_f32_16x16x32_bf16 v[36:39], v[174:177], v[198:201], v[36:39]
	v_mfma_f32_16x16x32_bf16 v[32:35], v[182:185], v[198:201], v[32:35]
	v_mfma_f32_16x16x32_bf16 v[20:23], v[174:177], v[210:213], v[20:23]
	v_mfma_f32_16x16x32_bf16 v[16:19], v[182:185], v[210:213], v[16:19]
	v_mfma_f32_16x16x32_bf16 v[4:7], v[174:177], v[218:221], v[4:7]
	v_mfma_f32_16x16x32_bf16 v[0:3], v[182:185], v[218:221], v[0:3]
	s_barrier
; #define PG8_STAGE(bufoff, gbase, voff) do { _Pragma("unroll") for (int _i = 0; _i < 2; ++_i) \
;         __builtin_amdgcn_global_load_lds((const unsigned*)((const char*)(gbase) + (voff)[_i]), (PG8_LAS unsigned*)(lds + (bufoff) + ldsw + _i * 8192), 16, 0, 0); } while (0)
; #define PG8_LDA(dst, b, h) do { _Pragma("unroll") for (int m = 0; m < 4; ++m) _Pragma("unroll") for (int k = 0; k < 2; ++k) dst[m][k] = *(const PG8_LAS bf16x8*)(lds + PG8_SA(b, h) + aoff + m * 2048 + k * 1024); } while (0)
; #define PG8_LDB(dst, b, h) do { _Pragma("unroll") for (int n = 0; n < 2; ++n) _Pragma("unroll") for (int k = 0; k < 2; ++k) dst[n][k] = *(const PG8_LAS bf16x8*)(lds + PG8_SB(b, h) + boff + n * 2048 + k * 1024); } while (0)
; #define PG8_MMA(ai, bj, At, Bt) do { __builtin_amdgcn_s_setprio(1); _Pragma("unroll") for (int m = 0; m < 4; ++m) _Pragma("unroll") for (int n = 0; n < 2; ++n) _Pragma("unroll") for (int k = 0; k < 2; ++k) \
;         acc[ai][bj][m][n] = __builtin_amdgcn_mfma_f32_16x16x32_bf16(Bt[n][k], At[m][k], acc[ai][bj][m][n], 0, 0, 0); __builtin_amdgcn_s_setprio(0); } while (0)
; #define PG8_WAIT_V(n) asm volatile("s_waitcnt vmcnt(" #n ")" ::: "memory")
; #define PG8_WAIT_L(n) asm volatile("s_waitcnt lgkmcnt(" #n ")" ::: "memory")
; #define PG8_BAR __builtin_amdgcn_s_barrier()
; #define PG8_SCHED __builtin_amdgcn_sched_barrier(0)
; template <class Epi, class Sched, bool ALIGN_EPI = false, bool SP2 = false>
; __device__ __forceinline__ void gemm_phase(PG8_LAS unsigned char* lds, const Gemm g, const Sched& S, const Epi& E) {
;     ...
;             PG8_LDB(B0, 1, 0); PG8_LDB(B1, 1, 1); PG8_SCHED; PG8_LDA(At, 1, 0); PG8_STAGE(PG8_SA(0, 1), a2 + hstep, voffA);
;             PG8_WAIT_V(8); PG8_WAIT_L(0); PG8_BAR; PG8_MMA(0, 0, At, B0); PG8_MMA(0, 1, At, B1); PG8_BAR; PG8_SCHED;
;             PG8_LDA(At, 1, 1); PG8_STAGE(PG8_SB(1, 0), b3, voffB); PG8_STAGE(PG8_SB(1, 1), b3 + hstep, voffB); PG8_STAGE(PG8_SA(1, 0), a3, voffA);
;             PG8_WAIT_V(8); PG8_WAIT_L(0); PG8_BAR; PG8_MMA(1, 0, At, B0); PG8_MMA(1, 1, At, B1); PG8_BAR; PG8_SCHED;
;     ...
;         }
;         if constexpr (ALIGN_EPI) { if (wr == 0) PG8_BAR; }
	s_add_i32 s65, 0, 0x18000
	s_add_i32 s66, 0, 0x1c000
	ds_read_b128 v[154:157], v240
	ds_read_b128 v[158:161], v240 offset:1024
	ds_read_b128 v[162:165], v240 offset:2048
	ds_read_b128 v[166:169], v240 offset:3072
	ds_read_b128 v[170:173], v241
	ds_read_b128 v[174:177], v241 offset:1024
	ds_read_b128 v[178:181], v241 offset:2048
	ds_read_b128 v[182:185], v241 offset:3072
	s_add_u32 s100, s46, 0x80
	s_addc_u32 s101, s47, 0
	s_add_u32 s46, s46, 0x40000
	s_addc_u32 s47, s47, 0
	s_mov_b32 m0, s50
	ds_read_b128 v[186:189], v151 offset:32768
	ds_read_b128 v[190:193], v151 offset:33792
	ds_read_b128 v[194:197], v151 offset:34816
	ds_read_b128 v[198:201], v151 offset:35840
	ds_read_b128 v[206:209], v151 offset:36864
	ds_read_b128 v[210:213], v151 offset:37888
	ds_read_b128 v[214:217], v151 offset:38912
	ds_read_b128 v[218:221], v151 offset:39936
	global_load_lds_dwordx4 v130, s[46:47]
	s_mov_b32 m0, s51
	s_nop 0
	global_load_lds_dwordx4 v134, s[46:47]
	s_waitcnt vmcnt(8)
	s_waitcnt lgkmcnt(0)
	s_barrier
	v_mfma_f32_16x16x32_bf16 v[124:127], v[154:157], v[186:189], v[124:127]
	v_mfma_f32_16x16x32_bf16 v[120:123], v[162:165], v[186:189], v[120:123]
	v_mfma_f32_16x16x32_bf16 v[108:111], v[154:157], v[194:197], v[108:111]
	v_mfma_f32_16x16x32_bf16 v[104:107], v[162:165], v[194:197], v[104:107]
	v_mfma_f32_16x16x32_bf16 v[92:95], v[154:157], v[206:209], v[92:95]
	v_mfma_f32_16x16x32_bf16 v[88:91], v[162:165], v[206:209], v[88:91]
	v_mfma_f32_16x16x32_bf16 v[76:79], v[154:157], v[214:217], v[76:79]
	v_mfma_f32_16x16x32_bf16 v[72:75], v[162:165], v[214:217], v[72:75]
	v_mfma_f32_16x16x32_bf16 v[124:127], v[158:161], v[190:193], v[124:127]
	v_mfma_f32_16x16x32_bf16 v[120:123], v[166:169], v[190:193], v[120:123]
	v_mfma_f32_16x16x32_bf16 v[108:111], v[158:161], v[198:201], v[108:111]
	v_mfma_f32_16x16x32_bf16 v[104:107], v[166:169], v[198:201], v[104:107]
	v_mfma_f32_16x16x32_bf16 v[92:95], v[158:161], v[210:213], v[92:95]
	v_mfma_f32_16x16x32_bf16 v[88:91], v[166:169], v[210:213], v[88:91]
	v_mfma_f32_16x16x32_bf16 v[76:79], v[158:161], v[218:221], v[76:79]
	v_mfma_f32_16x16x32_bf16 v[72:75], v[166:169], v[218:221], v[72:75]
	v_mfma_f32_16x16x32_bf16 v[116:119], v[170:173], v[186:189], v[116:119]
	v_mfma_f32_16x16x32_bf16 v[112:115], v[178:181], v[186:189], v[112:115]
	v_mfma_f32_16x16x32_bf16 v[100:103], v[170:173], v[194:197], v[100:103]
	v_mfma_f32_16x16x32_bf16 v[96:99], v[178:181], v[194:197], v[96:99]
	v_mfma_f32_16x16x32_bf16 v[84:87], v[170:173], v[206:209], v[84:87]
	v_mfma_f32_16x16x32_bf16 v[80:83], v[178:181], v[206:209], v[80:83]
	v_mfma_f32_16x16x32_bf16 v[68:71], v[170:173], v[214:217], v[68:71]
	v_mfma_f32_16x16x32_bf16 v[64:67], v[178:181], v[214:217], v[64:67]
	v_mfma_f32_16x16x32_bf16 v[116:119], v[174:177], v[190:193], v[116:119]
	v_mfma_f32_16x16x32_bf16 v[112:115], v[182:185], v[190:193], v[112:115]
	v_mfma_f32_16x16x32_bf16 v[100:103], v[174:177], v[198:201], v[100:103]
	v_mfma_f32_16x16x32_bf16 v[96:99], v[182:185], v[198:201], v[96:99]
	v_mfma_f32_16x16x32_bf16 v[84:87], v[174:177], v[210:213], v[84:87]
	v_mfma_f32_16x16x32_bf16 v[80:83], v[182:185], v[210:213], v[80:83]
	v_mfma_f32_16x16x32_bf16 v[68:71], v[174:177], v[218:221], v[68:71]
	v_mfma_f32_16x16x32_bf16 v[64:67], v[182:185], v[218:221], v[64:67]
	s_barrier
	s_add_i32 s46, s65, s13
	s_mov_b32 m0, s46
	ds_read_b128 v[186:189], v151 offset:49152
	ds_read_b128 v[190:193], v151 offset:50176
	ds_read_b128 v[194:197], v151 offset:51200
	ds_read_b128 v[198:201], v151 offset:52224
	ds_read_b128 v[206:209], v151 offset:53248
	ds_read_b128 v[210:213], v151 offset:54272
	ds_read_b128 v[214:217], v151 offset:55296
	ds_read_b128 v[218:221], v151 offset:56320
	global_load_lds_dwordx4 v132, s[98:99]
	s_add_i32 m0, s46, 0x2000
	s_add_u32 s44, s44, 0x40080
	s_addc_u32 s45, s45, 0
	s_add_i32 s46, s66, s13
	global_load_lds_dwordx4 v136, s[98:99]
	s_mov_b32 m0, s46
	s_nop 0
	global_load_lds_dwordx4 v132, s[44:45]
	s_add_i32 m0, s46, 0x2000
	s_nop 0
	global_load_lds_dwordx4 v136, s[44:45]
	s_mov_b32 m0, s54
	s_nop 0
	global_load_lds_dwordx4 v130, s[100:101]
	s_mov_b32 m0, s55
	s_nop 0
	global_load_lds_dwordx4 v134, s[100:101]
	s_waitcnt vmcnt(8)
	s_waitcnt lgkmcnt(0)
	s_barrier
	v_mfma_f32_16x16x32_bf16 v[60:63], v[154:157], v[186:189], v[60:63]
	v_mfma_f32_16x16x32_bf16 v[56:59], v[162:165], v[186:189], v[56:59]
	v_mfma_f32_16x16x32_bf16 v[44:47], v[154:157], v[194:197], v[44:47]
	v_mfma_f32_16x16x32_bf16 v[40:43], v[162:165], v[194:197], v[40:43]
	v_mfma_f32_16x16x32_bf16 v[28:31], v[154:157], v[206:209], v[28:31]
	v_mfma_f32_16x16x32_bf16 v[24:27], v[162:165], v[206:209], v[24:27]
	v_mfma_f32_16x16x32_bf16 v[12:15], v[154:157], v[214:217], v[12:15]
	v_mfma_f32_16x16x32_bf16 v[8:11], v[162:165], v[214:217], v[8:11]
	v_mfma_f32_16x16x32_bf16 v[60:63], v[158:161], v[190:193], v[60:63]
	v_mfma_f32_16x16x32_bf16 v[56:59], v[166:169], v[190:193], v[56:59]
	v_mfma_f32_16x16x32_bf16 v[44:47], v[158:161], v[198:201], v[44:47]
	v_mfma_f32_16x16x32_bf16 v[40:43], v[166:169], v[198:201], v[40:43]
	v_mfma_f32_16x16x32_bf16 v[28:31], v[158:161], v[210:213], v[28:31]
	v_mfma_f32_16x16x32_bf16 v[24:27], v[166:169], v[210:213], v[24:27]
	v_mfma_f32_16x16x32_bf16 v[12:15], v[158:161], v[218:221], v[12:15]
	v_mfma_f32_16x16x32_bf16 v[8:11], v[166:169], v[218:221], v[8:11]
	v_mfma_f32_16x16x32_bf16 v[52:55], v[170:173], v[186:189], v[52:55]
	v_mfma_f32_16x16x32_bf16 v[48:51], v[178:181], v[186:189], v[48:51]
	v_mfma_f32_16x16x32_bf16 v[36:39], v[170:173], v[194:197], v[36:39]
	v_mfma_f32_16x16x32_bf16 v[32:35], v[178:181], v[194:197], v[32:35]
	v_mfma_f32_16x16x32_bf16 v[20:23], v[170:173], v[206:209], v[20:23]
	v_mfma_f32_16x16x32_bf16 v[16:19], v[178:181], v[206:209], v[16:19]
	v_mfma_f32_16x16x32_bf16 v[4:7], v[170:173], v[214:217], v[4:7]
	v_mfma_f32_16x16x32_bf16 v[0:3], v[178:181], v[214:217], v[0:3]
	v_mfma_f32_16x16x32_bf16 v[52:55], v[174:177], v[190:193], v[52:55]
	v_mfma_f32_16x16x32_bf16 v[48:51], v[182:185], v[190:193], v[48:51]
	v_mfma_f32_16x16x32_bf16 v[36:39], v[174:177], v[198:201], v[36:39]
	v_mfma_f32_16x16x32_bf16 v[32:35], v[182:185], v[198:201], v[32:35]
	v_mfma_f32_16x16x32_bf16 v[20:23], v[174:177], v[210:213], v[20:23]
	v_mfma_f32_16x16x32_bf16 v[16:19], v[182:185], v[210:213], v[16:19]
	v_mfma_f32_16x16x32_bf16 v[4:7], v[174:177], v[218:221], v[4:7]
	v_mfma_f32_16x16x32_bf16 v[0:3], v[182:185], v[218:221], v[0:3]
	s_barrier
	s_add_i32 s64, s64, 2
	s_add_u32 s42, s42, 0x100
	s_addc_u32 s43, s43, 0
	s_add_u32 s62, s62, 0x100
	s_addc_u32 s63, s63, 0
	s_cmp_gt_u32 s64, 13
	s_cbranch_scc0 .LBB0_627
	s_and_b64 vcc, exec, s[30:31]
	s_cbranch_vccz .LBB0_630
	s_barrier

; #define PG8_STAGE(bufoff, gbase, voff) do { _Pragma("unroll") for (int _i = 0; _i < 2; ++_i) \
;         __builtin_amdgcn_global_load_lds((const unsigned*)((const char*)(gbase) + (voff)[_i]), (PG8_LAS unsigned*)(lds + (bufoff) + ldsw + _i * 8192), 16, 0, 0); } while (0)
; #define PG8_LDA(dst, b, h) do { _Pragma("unroll") for (int m = 0; m < 4; ++m) _Pragma("unroll") for (int k = 0; k < 2; ++k) dst[m][k] = *(const PG8_LAS bf16x8*)(lds + PG8_SA(b, h) + aoff + m * 2048 + k * 1024); } while (0)
; #define PG8_LDB(dst, b, h) do { _Pragma("unroll") for (int n = 0; n < 2; ++n) _Pragma("unroll") for (int k = 0; k < 2; ++k) dst[n][k] = *(const PG8_LAS bf16x8*)(lds + PG8_SB(b, h) + boff + n * 2048 + k * 1024); } while (0)
; #define PG8_MMA(ai, bj, At, Bt) do { __builtin_amdgcn_s_setprio(1); _Pragma("unroll") for (int m = 0; m < 4; ++m) _Pragma("unroll") for (int n = 0; n < 2; ++n) _Pragma("unroll") for (int k = 0; k < 2; ++k) \
;         acc[ai][bj][m][n] = __builtin_amdgcn_mfma_f32_16x16x32_bf16(Bt[n][k], At[m][k], acc[ai][bj][m][n], 0, 0, 0); __builtin_amdgcn_s_setprio(0); } while (0)
; #define PG8_WAIT_V(n) asm volatile("s_waitcnt vmcnt(" #n ")" ::: "memory")
; #define PG8_WAIT_L(n) asm volatile("s_waitcnt lgkmcnt(" #n ")" ::: "memory")
; #define PG8_BAR __builtin_amdgcn_s_barrier()
; #define PG8_SCHED __builtin_amdgcn_sched_barrier(0)
; template <class Epi, class Sched, bool ALIGN_EPI = false, bool SP2 = false>
; __device__ __forceinline__ void gemm_phase(PG8_LAS unsigned char* lds, const Gemm g, const Sched& S, const Epi& E) {
;     ...
;             PG8_LDB(B0, 0, 0); PG8_LDB(B1, 0, 1); PG8_SCHED; PG8_LDA(At, 0, 0); PG8_STAGE(PG8_SA(1, 1), a1 + hstep, voffA);
;             PG8_WAIT_V(8); PG8_WAIT_L(0); PG8_BAR; PG8_MMA(0, 0, At, B0); PG8_MMA(0, 1, At, B1); PG8_BAR; PG8_SCHED;
;             PG8_LDA(At, 0, 1); PG8_STAGE(PG8_SB(0, 0), b2, voffB); PG8_STAGE(PG8_SB(0, 1), b2 + hstep, voffB); PG8_STAGE(PG8_SA(0, 0), a2, voffA);
;             PG8_WAIT_V(8); PG8_WAIT_L(0); PG8_BAR; PG8_MMA(1, 0, At, B0); PG8_MMA(1, 1, At, B1); PG8_BAR; PG8_SCHED;
.LBB0_798:
	ds_read_b128 v[146:149], v152
	ds_read_b128 v[156:159], v152 offset:1024
	ds_read_b128 v[160:163], v152 offset:2048
	ds_read_b128 v[164:167], v152 offset:3072
	ds_read_b128 v[168:171], v153
	ds_read_b128 v[172:175], v153 offset:1024
	ds_read_b128 v[176:179], v153 offset:2048
	ds_read_b128 v[180:183], v153 offset:3072
	s_add_u32 s46, s44, 0xfffc0080
	s_addc_u32 s47, s45, -1
	s_cmp_eq_u32 s63, 12
	s_cselect_b32 s49, s35, s47
	s_cselect_b32 s48, s41, s46
	s_cselect_b32 s47, s31, s62
	s_cselect_b32 s46, s60, s61
	s_add_i32 m0, s43, 0xc000
	ds_read_b128 v[184:187], v154
	ds_read_b128 v[188:191], v154 offset:1024
	ds_read_b128 v[192:195], v154 offset:2048
	ds_read_b128 v[196:199], v154 offset:3072
	ds_read_b128 v[200:203], v154 offset:4096
	ds_read_b128 v[206:209], v154 offset:5120
	ds_read_b128 v[210:213], v154 offset:6144
	ds_read_b128 v[214:217], v154 offset:7168
	global_load_lds_dwordx4 v138, s[44:45]
	s_add_i32 m0, s43, 0xe000
	s_nop 0
	global_load_lds_dwordx4 v140, s[44:45]
	s_waitcnt vmcnt(8)
	s_waitcnt lgkmcnt(0)
	s_barrier
	v_mfma_f32_16x16x32_bf16 v[124:127], v[146:149], v[184:187], v[124:127]
	v_mfma_f32_16x16x32_bf16 v[120:123], v[160:163], v[184:187], v[120:123]
	v_mfma_f32_16x16x32_bf16 v[108:111], v[146:149], v[192:195], v[108:111]
	v_mfma_f32_16x16x32_bf16 v[104:107], v[160:163], v[192:195], v[104:107]
	v_mfma_f32_16x16x32_bf16 v[92:95], v[146:149], v[200:203], v[92:95]
	v_mfma_f32_16x16x32_bf16 v[88:91], v[160:163], v[200:203], v[88:91]
	v_mfma_f32_16x16x32_bf16 v[76:79], v[146:149], v[210:213], v[76:79]
	v_mfma_f32_16x16x32_bf16 v[72:75], v[160:163], v[210:213], v[72:75]
	v_mfma_f32_16x16x32_bf16 v[124:127], v[156:159], v[188:191], v[124:127]
	v_mfma_f32_16x16x32_bf16 v[120:123], v[164:167], v[188:191], v[120:123]
	v_mfma_f32_16x16x32_bf16 v[108:111], v[156:159], v[196:199], v[108:111]
	v_mfma_f32_16x16x32_bf16 v[104:107], v[164:167], v[196:199], v[104:107]
	v_mfma_f32_16x16x32_bf16 v[92:95], v[156:159], v[206:209], v[92:95]
	v_mfma_f32_16x16x32_bf16 v[88:91], v[164:167], v[206:209], v[88:91]
	v_mfma_f32_16x16x32_bf16 v[76:79], v[156:159], v[214:217], v[76:79]
	v_mfma_f32_16x16x32_bf16 v[72:75], v[164:167], v[214:217], v[72:75]
	v_mfma_f32_16x16x32_bf16 v[116:119], v[168:171], v[184:187], v[116:119]
	v_mfma_f32_16x16x32_bf16 v[112:115], v[176:179], v[184:187], v[112:115]
	v_mfma_f32_16x16x32_bf16 v[100:103], v[168:171], v[192:195], v[100:103]
	v_mfma_f32_16x16x32_bf16 v[96:99], v[176:179], v[192:195], v[96:99]
	v_mfma_f32_16x16x32_bf16 v[84:87], v[168:171], v[200:203], v[84:87]
	v_mfma_f32_16x16x32_bf16 v[80:83], v[176:179], v[200:203], v[80:83]
	v_mfma_f32_16x16x32_bf16 v[68:71], v[168:171], v[210:213], v[68:71]
	v_mfma_f32_16x16x32_bf16 v[64:67], v[176:179], v[210:213], v[64:67]
	v_mfma_f32_16x16x32_bf16 v[116:119], v[172:175], v[188:191], v[116:119]
	v_mfma_f32_16x16x32_bf16 v[112:115], v[180:183], v[188:191], v[112:115]
	v_mfma_f32_16x16x32_bf16 v[100:103], v[172:175], v[196:199], v[100:103]
	v_mfma_f32_16x16x32_bf16 v[96:99], v[180:183], v[196:199], v[96:99]
	v_mfma_f32_16x16x32_bf16 v[84:87], v[172:175], v[206:209], v[84:87]
	v_mfma_f32_16x16x32_bf16 v[80:83], v[180:183], v[206:209], v[80:83]
	v_mfma_f32_16x16x32_bf16 v[68:71], v[172:175], v[214:217], v[68:71]
	v_mfma_f32_16x16x32_bf16 v[64:67], v[180:183], v[214:217], v[64:67]
	s_barrier
	s_add_i32 s64, s58, s33
	s_mov_b32 m0, s64
	ds_read_b128 v[184:187], v154 offset:16384
	ds_read_b128 v[188:191], v154 offset:17408
	ds_read_b128 v[192:195], v154 offset:18432
	ds_read_b128 v[196:199], v154 offset:19456
	ds_read_b128 v[200:203], v154 offset:20480
	ds_read_b128 v[206:209], v154 offset:21504
	ds_read_b128 v[210:213], v154 offset:22528
	ds_read_b128 v[214:217], v154 offset:23552
	global_load_lds_dwordx4 v132, s[46:47]
	s_add_i32 m0, s64, 0x2000
	s_add_u32 s98, s46, 0x80
	s_addc_u32 s99, s47, 0
	s_add_u32 s64, s46, 0x40000
	s_addc_u32 s65, s47, 0
	s_add_i32 s66, s59, s33
	global_load_lds_dwordx4 v136, s[46:47]
	s_mov_b32 m0, s66
	s_nop 0
	global_load_lds_dwordx4 v132, s[64:65]
	s_add_i32 m0, s66, 0x2000
	s_nop 0
	global_load_lds_dwordx4 v136, s[64:65]
	s_mov_b32 m0, s43
	s_nop 0
	global_load_lds_dwordx4 v130, s[48:49]
	s_mov_b32 m0, s50
	s_nop 0
	global_load_lds_dwordx4 v134, s[48:49]
	s_waitcnt vmcnt(8)
	s_waitcnt lgkmcnt(0)
	s_barrier
	v_mfma_f32_16x16x32_bf16 v[60:63], v[146:149], v[184:187], v[60:63]
	v_mfma_f32_16x16x32_bf16 v[56:59], v[160:163], v[184:187], v[56:59]
	v_mfma_f32_16x16x32_bf16 v[44:47], v[146:149], v[192:195], v[44:47]
	v_mfma_f32_16x16x32_bf16 v[40:43], v[160:163], v[192:195], v[40:43]
	v_mfma_f32_16x16x32_bf16 v[28:31], v[146:149], v[200:203], v[28:31]
	v_mfma_f32_16x16x32_bf16 v[24:27], v[160:163], v[200:203], v[24:27]
	v_mfma_f32_16x16x32_bf16 v[12:15], v[146:149], v[210:213], v[12:15]
	v_mfma_f32_16x16x32_bf16 v[8:11], v[160:163], v[210:213], v[8:11]
	v_mfma_f32_16x16x32_bf16 v[60:63], v[156:159], v[188:191], v[60:63]
	v_mfma_f32_16x16x32_bf16 v[56:59], v[164:167], v[188:191], v[56:59]
	v_mfma_f32_16x16x32_bf16 v[44:47], v[156:159], v[196:199], v[44:47]
	v_mfma_f32_16x16x32_bf16 v[40:43], v[164:167], v[196:199], v[40:43]
	v_mfma_f32_16x16x32_bf16 v[28:31], v[156:159], v[206:209], v[28:31]
	v_mfma_f32_16x16x32_bf16 v[24:27], v[164:167], v[206:209], v[24:27]
	v_mfma_f32_16x16x32_bf16 v[12:15], v[156:159], v[214:217], v[12:15]
	v_mfma_f32_16x16x32_bf16 v[8:11], v[164:167], v[214:217], v[8:11]
	v_mfma_f32_16x16x32_bf16 v[52:55], v[168:171], v[184:187], v[52:55]
	v_mfma_f32_16x16x32_bf16 v[48:51], v[176:179], v[184:187], v[48:51]
	v_mfma_f32_16x16x32_bf16 v[36:39], v[168:171], v[192:195], v[36:39]
	v_mfma_f32_16x16x32_bf16 v[32:35], v[176:179], v[192:195], v[32:35]
	v_mfma_f32_16x16x32_bf16 v[20:23], v[168:171], v[200:203], v[20:23]
	v_mfma_f32_16x16x32_bf16 v[16:19], v[176:179], v[200:203], v[16:19]
	v_mfma_f32_16x16x32_bf16 v[4:7], v[168:171], v[210:213], v[4:7]
	v_mfma_f32_16x16x32_bf16 v[0:3], v[176:179], v[210:213], v[0:3]
	v_mfma_f32_16x16x32_bf16 v[52:55], v[172:175], v[188:191], v[52:55]
	v_mfma_f32_16x16x32_bf16 v[48:51], v[180:183], v[188:191], v[48:51]
	v_mfma_f32_16x16x32_bf16 v[36:39], v[172:175], v[196:199], v[36:39]
	v_mfma_f32_16x16x32_bf16 v[32:35], v[180:183], v[196:199], v[32:35]
	v_mfma_f32_16x16x32_bf16 v[20:23], v[172:175], v[206:209], v[20:23]
	v_mfma_f32_16x16x32_bf16 v[16:19], v[180:183], v[206:209], v[16:19]
	v_mfma_f32_16x16x32_bf16 v[4:7], v[172:175], v[214:217], v[4:7]
	v_mfma_f32_16x16x32_bf16 v[0:3], v[180:183], v[214:217], v[0:3]
	s_barrier
; #define PG8_STAGE(bufoff, gbase, voff) do { _Pragma("unroll") for (int _i = 0; _i < 2; ++_i) \
;         __builtin_amdgcn_global_load_lds((const unsigned*)((const char*)(gbase) + (voff)[_i]), (PG8_LAS unsigned*)(lds + (bufoff) + ldsw + _i * 8192), 16, 0, 0); } while (0)
; #define PG8_LDA(dst, b, h) do { _Pragma("unroll") for (int m = 0; m < 4; ++m) _Pragma("unroll") for (int k = 0; k < 2; ++k) dst[m][k] = *(const PG8_LAS bf16x8*)(lds + PG8_SA(b, h) + aoff + m * 2048 + k * 1024); } while (0)
; #define PG8_LDB(dst, b, h) do { _Pragma("unroll") for (int n = 0; n < 2; ++n) _Pragma("unroll") for (int k = 0; k < 2; ++k) dst[n][k] = *(const PG8_LAS bf16x8*)(lds + PG8_SB(b, h) + boff + n * 2048 + k * 1024); } while (0)
; #define PG8_MMA(ai, bj, At, Bt) do { __builtin_amdgcn_s_setprio(1); _Pragma("unroll") for (int m = 0; m < 4; ++m) _Pragma("unroll") for (int n = 0; n < 2; ++n) _Pragma("unroll") for (int k = 0; k < 2; ++k) \
;         acc[ai][bj][m][n] = __builtin_amdgcn_mfma_f32_16x16x32_bf16(Bt[n][k], At[m][k], acc[ai][bj][m][n], 0, 0, 0); __builtin_amdgcn_s_setprio(0); } while (0)
; #define PG8_WAIT_V(n) asm volatile("s_waitcnt vmcnt(" #n ")" ::: "memory")
; #define PG8_WAIT_L(n) asm volatile("s_waitcnt lgkmcnt(" #n ")" ::: "memory")
; #define PG8_BAR __builtin_amdgcn_s_barrier()
; #define PG8_SCHED __builtin_amdgcn_sched_barrier(0)
; template <class Epi, class Sched, bool ALIGN_EPI = false, bool SP2 = false>
; __device__ __forceinline__ void gemm_phase(PG8_LAS unsigned char* lds, const Gemm g, const Sched& S, const Epi& E) {
;     ...
;             PG8_LDB(B0, 1, 0); PG8_LDB(B1, 1, 1); PG8_SCHED; PG8_LDA(At, 1, 0); PG8_STAGE(PG8_SA(0, 1), a2 + hstep, voffA);
;             PG8_WAIT_V(8); PG8_WAIT_L(0); PG8_BAR; PG8_MMA(0, 0, At, B0); PG8_MMA(0, 1, At, B1); PG8_BAR; PG8_SCHED;
;             PG8_LDA(At, 1, 1); PG8_STAGE(PG8_SB(1, 0), b3, voffB); PG8_STAGE(PG8_SB(1, 1), b3 + hstep, voffB); PG8_STAGE(PG8_SA(1, 0), a3, voffA);
;             PG8_WAIT_V(8); PG8_WAIT_L(0); PG8_BAR; PG8_MMA(1, 0, At, B0); PG8_MMA(1, 1, At, B1); PG8_BAR; PG8_SCHED;
;     ...
;         }
;         if constexpr (ALIGN_EPI) { if (wr == 0) PG8_BAR; }
	s_add_i32 s64, 0, 0x18000
	s_add_i32 s65, 0, 0x1c000
	ds_read_b128 v[146:149], v240
	ds_read_b128 v[156:159], v240 offset:1024
	ds_read_b128 v[160:163], v240 offset:2048
	ds_read_b128 v[164:167], v240 offset:3072
	ds_read_b128 v[168:171], v241
	ds_read_b128 v[172:175], v241 offset:1024
	ds_read_b128 v[176:179], v241 offset:2048
	ds_read_b128 v[180:183], v241 offset:3072
	s_add_u32 s100, s48, 0x80
	s_addc_u32 s101, s49, 0
	s_add_u32 s48, s48, 0x40000
	s_addc_u32 s49, s49, 0
	s_mov_b32 m0, s51
	ds_read_b128 v[184:187], v154 offset:32768
	ds_read_b128 v[188:191], v154 offset:33792
	ds_read_b128 v[192:195], v154 offset:34816
	ds_read_b128 v[196:199], v154 offset:35840
	ds_read_b128 v[200:203], v154 offset:36864
	ds_read_b128 v[206:209], v154 offset:37888
	ds_read_b128 v[210:213], v154 offset:38912
	ds_read_b128 v[214:217], v154 offset:39936
	global_load_lds_dwordx4 v130, s[48:49]
	s_mov_b32 m0, s52
	s_nop 0
	global_load_lds_dwordx4 v134, s[48:49]
	s_waitcnt vmcnt(8)
	s_waitcnt lgkmcnt(0)
	s_barrier
	v_mfma_f32_16x16x32_bf16 v[124:127], v[146:149], v[184:187], v[124:127]
	v_mfma_f32_16x16x32_bf16 v[120:123], v[160:163], v[184:187], v[120:123]
	v_mfma_f32_16x16x32_bf16 v[108:111], v[146:149], v[192:195], v[108:111]
	v_mfma_f32_16x16x32_bf16 v[104:107], v[160:163], v[192:195], v[104:107]
	v_mfma_f32_16x16x32_bf16 v[92:95], v[146:149], v[200:203], v[92:95]
	v_mfma_f32_16x16x32_bf16 v[88:91], v[160:163], v[200:203], v[88:91]
	v_mfma_f32_16x16x32_bf16 v[76:79], v[146:149], v[210:213], v[76:79]
	v_mfma_f32_16x16x32_bf16 v[72:75], v[160:163], v[210:213], v[72:75]
	v_mfma_f32_16x16x32_bf16 v[124:127], v[156:159], v[188:191], v[124:127]
	v_mfma_f32_16x16x32_bf16 v[120:123], v[164:167], v[188:191], v[120:123]
	v_mfma_f32_16x16x32_bf16 v[108:111], v[156:159], v[196:199], v[108:111]
	v_mfma_f32_16x16x32_bf16 v[104:107], v[164:167], v[196:199], v[104:107]
	v_mfma_f32_16x16x32_bf16 v[92:95], v[156:159], v[206:209], v[92:95]
	v_mfma_f32_16x16x32_bf16 v[88:91], v[164:167], v[206:209], v[88:91]
	v_mfma_f32_16x16x32_bf16 v[76:79], v[156:159], v[214:217], v[76:79]
	v_mfma_f32_16x16x32_bf16 v[72:75], v[164:167], v[214:217], v[72:75]
	v_mfma_f32_16x16x32_bf16 v[116:119], v[168:171], v[184:187], v[116:119]
	v_mfma_f32_16x16x32_bf16 v[112:115], v[176:179], v[184:187], v[112:115]
	v_mfma_f32_16x16x32_bf16 v[100:103], v[168:171], v[192:195], v[100:103]
	v_mfma_f32_16x16x32_bf16 v[96:99], v[176:179], v[192:195], v[96:99]
	v_mfma_f32_16x16x32_bf16 v[84:87], v[168:171], v[200:203], v[84:87]
	v_mfma_f32_16x16x32_bf16 v[80:83], v[176:179], v[200:203], v[80:83]
	v_mfma_f32_16x16x32_bf16 v[68:71], v[168:171], v[210:213], v[68:71]
	v_mfma_f32_16x16x32_bf16 v[64:67], v[176:179], v[210:213], v[64:67]
	v_mfma_f32_16x16x32_bf16 v[116:119], v[172:175], v[188:191], v[116:119]
	v_mfma_f32_16x16x32_bf16 v[112:115], v[180:183], v[188:191], v[112:115]
	v_mfma_f32_16x16x32_bf16 v[100:103], v[172:175], v[196:199], v[100:103]
	v_mfma_f32_16x16x32_bf16 v[96:99], v[180:183], v[196:199], v[96:99]
	v_mfma_f32_16x16x32_bf16 v[84:87], v[172:175], v[206:209], v[84:87]
	v_mfma_f32_16x16x32_bf16 v[80:83], v[180:183], v[206:209], v[80:83]
	v_mfma_f32_16x16x32_bf16 v[68:71], v[172:175], v[214:217], v[68:71]
	v_mfma_f32_16x16x32_bf16 v[64:67], v[180:183], v[214:217], v[64:67]
	s_barrier
	s_add_i32 s48, s64, s33
	s_mov_b32 m0, s48
	ds_read_b128 v[184:187], v154 offset:49152
	ds_read_b128 v[188:191], v154 offset:50176
	ds_read_b128 v[192:195], v154 offset:51200
	ds_read_b128 v[196:199], v154 offset:52224
	ds_read_b128 v[200:203], v154 offset:53248
	ds_read_b128 v[206:209], v154 offset:54272
	ds_read_b128 v[210:213], v154 offset:55296
	ds_read_b128 v[214:217], v154 offset:56320
	global_load_lds_dwordx4 v132, s[98:99]
	s_add_i32 m0, s48, 0x2000
	s_add_u32 s46, s46, 0x40080
	s_addc_u32 s47, s47, 0
	s_add_i32 s48, s65, s33
	global_load_lds_dwordx4 v136, s[98:99]
	s_mov_b32 m0, s48
	s_nop 0
	global_load_lds_dwordx4 v132, s[46:47]
	s_add_i32 m0, s48, 0x2000
	s_nop 0
	global_load_lds_dwordx4 v136, s[46:47]
	s_mov_b32 m0, s54
	s_nop 0
	global_load_lds_dwordx4 v130, s[100:101]
	s_mov_b32 m0, s55
	s_nop 0
	global_load_lds_dwordx4 v134, s[100:101]
	s_waitcnt vmcnt(8)
	s_waitcnt lgkmcnt(0)
	s_barrier
	v_mfma_f32_16x16x32_bf16 v[60:63], v[146:149], v[184:187], v[60:63]
	v_mfma_f32_16x16x32_bf16 v[56:59], v[160:163], v[184:187], v[56:59]
	v_mfma_f32_16x16x32_bf16 v[44:47], v[146:149], v[192:195], v[44:47]
	v_mfma_f32_16x16x32_bf16 v[40:43], v[160:163], v[192:195], v[40:43]
	v_mfma_f32_16x16x32_bf16 v[28:31], v[146:149], v[200:203], v[28:31]
	v_mfma_f32_16x16x32_bf16 v[24:27], v[160:163], v[200:203], v[24:27]
	v_mfma_f32_16x16x32_bf16 v[12:15], v[146:149], v[210:213], v[12:15]
	v_mfma_f32_16x16x32_bf16 v[8:11], v[160:163], v[210:213], v[8:11]
	v_mfma_f32_16x16x32_bf16 v[60:63], v[156:159], v[188:191], v[60:63]
	v_mfma_f32_16x16x32_bf16 v[56:59], v[164:167], v[188:191], v[56:59]
	v_mfma_f32_16x16x32_bf16 v[44:47], v[156:159], v[196:199], v[44:47]
	v_mfma_f32_16x16x32_bf16 v[40:43], v[164:167], v[196:199], v[40:43]
	v_mfma_f32_16x16x32_bf16 v[28:31], v[156:159], v[206:209], v[28:31]
	v_mfma_f32_16x16x32_bf16 v[24:27], v[164:167], v[206:209], v[24:27]
	v_mfma_f32_16x16x32_bf16 v[12:15], v[156:159], v[214:217], v[12:15]
	v_mfma_f32_16x16x32_bf16 v[8:11], v[164:167], v[214:217], v[8:11]
	v_mfma_f32_16x16x32_bf16 v[52:55], v[168:171], v[184:187], v[52:55]
	v_mfma_f32_16x16x32_bf16 v[48:51], v[176:179], v[184:187], v[48:51]
	v_mfma_f32_16x16x32_bf16 v[36:39], v[168:171], v[192:195], v[36:39]
	v_mfma_f32_16x16x32_bf16 v[32:35], v[176:179], v[192:195], v[32:35]
	v_mfma_f32_16x16x32_bf16 v[20:23], v[168:171], v[200:203], v[20:23]
	v_mfma_f32_16x16x32_bf16 v[16:19], v[176:179], v[200:203], v[16:19]
	v_mfma_f32_16x16x32_bf16 v[4:7], v[168:171], v[210:213], v[4:7]
	v_mfma_f32_16x16x32_bf16 v[0:3], v[176:179], v[210:213], v[0:3]
	v_mfma_f32_16x16x32_bf16 v[52:55], v[172:175], v[188:191], v[52:55]
	v_mfma_f32_16x16x32_bf16 v[48:51], v[180:183], v[188:191], v[48:51]
	v_mfma_f32_16x16x32_bf16 v[36:39], v[172:175], v[196:199], v[36:39]
	v_mfma_f32_16x16x32_bf16 v[32:35], v[180:183], v[196:199], v[32:35]
	v_mfma_f32_16x16x32_bf16 v[20:23], v[172:175], v[206:209], v[20:23]
	v_mfma_f32_16x16x32_bf16 v[16:19], v[180:183], v[206:209], v[16:19]
	v_mfma_f32_16x16x32_bf16 v[4:7], v[172:175], v[214:217], v[4:7]
	v_mfma_f32_16x16x32_bf16 v[0:3], v[180:183], v[214:217], v[0:3]
	s_barrier
	s_add_i32 s63, s63, 2
	s_add_u32 s44, s44, 0x100
	s_addc_u32 s45, s45, 0
	s_add_u32 s61, s61, 0x100
	s_addc_u32 s62, s62, 0
	s_cmp_gt_u32 s63, 13
	s_cbranch_scc0 .LBB0_798
	s_and_b64 vcc, exec, s[28:29]
	s_cbranch_vccz .LBB0_801
	s_barrier

; #define PG8_STAGE(bufoff, gbase, voff) do { _Pragma("unroll") for (int _i = 0; _i < 2; ++_i) \
;         __builtin_amdgcn_global_load_lds((const unsigned*)((const char*)(gbase) + (voff)[_i]), (PG8_LAS unsigned*)(lds + (bufoff) + ldsw + _i * 8192), 16, 0, 0); } while (0)
; #define PG8_LDA(dst, b, h) do { _Pragma("unroll") for (int m = 0; m < 4; ++m) _Pragma("unroll") for (int k = 0; k < 2; ++k) dst[m][k] = *(const PG8_LAS bf16x8*)(lds + PG8_SA(b, h) + aoff + m * 2048 + k * 1024); } while (0)
; #define PG8_LDB(dst, b, h) do { _Pragma("unroll") for (int n = 0; n < 2; ++n) _Pragma("unroll") for (int k = 0; k < 2; ++k) dst[n][k] = *(const PG8_LAS bf16x8*)(lds + PG8_SB(b, h) + boff + n * 2048 + k * 1024); } while (0)
; #define PG8_MMA(ai, bj, At, Bt) do { __builtin_amdgcn_s_setprio(1); _Pragma("unroll") for (int m = 0; m < 4; ++m) _Pragma("unroll") for (int n = 0; n < 2; ++n) _Pragma("unroll") for (int k = 0; k < 2; ++k) \
;         acc[ai][bj][m][n] = __builtin_amdgcn_mfma_f32_16x16x32_bf16(Bt[n][k], At[m][k], acc[ai][bj][m][n], 0, 0, 0); __builtin_amdgcn_s_setprio(0); } while (0)
; #define PG8_WAIT_V(n) asm volatile("s_waitcnt vmcnt(" #n ")" ::: "memory")
; #define PG8_WAIT_L(n) asm volatile("s_waitcnt lgkmcnt(" #n ")" ::: "memory")
; #define PG8_BAR __builtin_amdgcn_s_barrier()
; #define PG8_SCHED __builtin_amdgcn_sched_barrier(0)
; template <class Epi, class Sched, bool ALIGN_EPI = false, bool SP2 = false>
; __device__ __forceinline__ void gemm_phase(PG8_LAS unsigned char* lds, const Gemm g, const Sched& S, const Epi& E) {
;     ...
;             PG8_LDB(B0, 0, 0); PG8_LDB(B1, 0, 1); PG8_SCHED; PG8_LDA(At, 0, 0); PG8_STAGE(PG8_SA(1, 1), a1 + hstep, voffA);
;             PG8_WAIT_V(8); PG8_WAIT_L(0); PG8_BAR; PG8_MMA(0, 0, At, B0); PG8_MMA(0, 1, At, B1); PG8_BAR; PG8_SCHED;
;             PG8_LDA(At, 0, 1); PG8_STAGE(PG8_SB(0, 0), b2, voffB); PG8_STAGE(PG8_SB(0, 1), b2 + hstep, voffB); PG8_STAGE(PG8_SA(0, 0), a2, voffA);
;             PG8_WAIT_V(8); PG8_WAIT_L(0); PG8_BAR; PG8_MMA(1, 0, At, B0); PG8_MMA(1, 1, At, B1); PG8_BAR; PG8_SCHED;
.LBB0_905:
	ds_read_b128 v[146:149], v151
	ds_read_b128 v[156:159], v151 offset:1024
	ds_read_b128 v[160:163], v151 offset:2048
	ds_read_b128 v[164:167], v151 offset:3072
	ds_read_b128 v[168:171], v152
	ds_read_b128 v[172:175], v152 offset:1024
	ds_read_b128 v[176:179], v152 offset:2048
	ds_read_b128 v[180:183], v152 offset:3072
	s_add_u32 s42, s40, 0xfffc0080
	s_addc_u32 s43, s41, -1
	s_cmp_eq_u32 s62, 12
	s_cselect_b32 s45, s35, s43
	s_cselect_b32 s44, s58, s42
	s_cselect_b32 s43, s31, s61
	s_cselect_b32 s42, s59, s60
	s_add_i32 m0, s46, 0xc000
	ds_read_b128 v[184:187], v153
	ds_read_b128 v[188:191], v153 offset:1024
	ds_read_b128 v[192:195], v153 offset:2048
	ds_read_b128 v[196:199], v153 offset:3072
	ds_read_b128 v[200:203], v153 offset:4096
	ds_read_b128 v[206:209], v153 offset:5120
	ds_read_b128 v[210:213], v153 offset:6144
	ds_read_b128 v[214:217], v153 offset:7168
	global_load_lds_dwordx4 v138, s[40:41]
	s_add_i32 m0, s46, 0xe000
	s_nop 0
	global_load_lds_dwordx4 v140, s[40:41]
	s_waitcnt vmcnt(8)
	s_waitcnt lgkmcnt(0)
	s_barrier
	v_mfma_f32_16x16x32_bf16 v[124:127], v[146:149], v[184:187], v[124:127]
	v_mfma_f32_16x16x32_bf16 v[120:123], v[160:163], v[184:187], v[120:123]
	v_mfma_f32_16x16x32_bf16 v[108:111], v[146:149], v[192:195], v[108:111]
	v_mfma_f32_16x16x32_bf16 v[104:107], v[160:163], v[192:195], v[104:107]
	v_mfma_f32_16x16x32_bf16 v[92:95], v[146:149], v[200:203], v[92:95]
	v_mfma_f32_16x16x32_bf16 v[88:91], v[160:163], v[200:203], v[88:91]
	v_mfma_f32_16x16x32_bf16 v[76:79], v[146:149], v[210:213], v[76:79]
	v_mfma_f32_16x16x32_bf16 v[72:75], v[160:163], v[210:213], v[72:75]
	v_mfma_f32_16x16x32_bf16 v[124:127], v[156:159], v[188:191], v[124:127]
	v_mfma_f32_16x16x32_bf16 v[120:123], v[164:167], v[188:191], v[120:123]
	v_mfma_f32_16x16x32_bf16 v[108:111], v[156:159], v[196:199], v[108:111]
	v_mfma_f32_16x16x32_bf16 v[104:107], v[164:167], v[196:199], v[104:107]
	v_mfma_f32_16x16x32_bf16 v[92:95], v[156:159], v[206:209], v[92:95]
	v_mfma_f32_16x16x32_bf16 v[88:91], v[164:167], v[206:209], v[88:91]
	v_mfma_f32_16x16x32_bf16 v[76:79], v[156:159], v[214:217], v[76:79]
	v_mfma_f32_16x16x32_bf16 v[72:75], v[164:167], v[214:217], v[72:75]
	v_mfma_f32_16x16x32_bf16 v[116:119], v[168:171], v[184:187], v[116:119]
	v_mfma_f32_16x16x32_bf16 v[112:115], v[176:179], v[184:187], v[112:115]
	v_mfma_f32_16x16x32_bf16 v[100:103], v[168:171], v[192:195], v[100:103]
	v_mfma_f32_16x16x32_bf16 v[96:99], v[176:179], v[192:195], v[96:99]
	v_mfma_f32_16x16x32_bf16 v[84:87], v[168:171], v[200:203], v[84:87]
	v_mfma_f32_16x16x32_bf16 v[80:83], v[176:179], v[200:203], v[80:83]
	v_mfma_f32_16x16x32_bf16 v[68:71], v[168:171], v[210:213], v[68:71]
	v_mfma_f32_16x16x32_bf16 v[64:67], v[176:179], v[210:213], v[64:67]
	v_mfma_f32_16x16x32_bf16 v[116:119], v[172:175], v[188:191], v[116:119]
	v_mfma_f32_16x16x32_bf16 v[112:115], v[180:183], v[188:191], v[112:115]
	v_mfma_f32_16x16x32_bf16 v[100:103], v[172:175], v[196:199], v[100:103]
	v_mfma_f32_16x16x32_bf16 v[96:99], v[180:183], v[196:199], v[96:99]
	v_mfma_f32_16x16x32_bf16 v[84:87], v[172:175], v[206:209], v[84:87]
	v_mfma_f32_16x16x32_bf16 v[80:83], v[180:183], v[206:209], v[80:83]
	v_mfma_f32_16x16x32_bf16 v[68:71], v[172:175], v[214:217], v[68:71]
	v_mfma_f32_16x16x32_bf16 v[64:67], v[180:183], v[214:217], v[64:67]
	s_barrier
	s_add_i32 s63, s55, s33
	s_mov_b32 m0, s63
	ds_read_b128 v[184:187], v153 offset:16384
	ds_read_b128 v[188:191], v153 offset:17408
	ds_read_b128 v[192:195], v153 offset:18432
	ds_read_b128 v[196:199], v153 offset:19456
	ds_read_b128 v[200:203], v153 offset:20480
	ds_read_b128 v[206:209], v153 offset:21504
	ds_read_b128 v[210:213], v153 offset:22528
	ds_read_b128 v[214:217], v153 offset:23552
	global_load_lds_dwordx4 v132, s[42:43]
	s_add_i32 m0, s63, 0x2000
	s_add_u32 s98, s42, 0x80
	s_addc_u32 s99, s43, 0
	s_add_u32 s64, s42, 0x40000
	s_addc_u32 s65, s43, 0
	s_add_i32 s63, s56, s33
	global_load_lds_dwordx4 v136, s[42:43]
	s_mov_b32 m0, s63
	s_nop 0
	global_load_lds_dwordx4 v132, s[64:65]
	s_add_i32 m0, s63, 0x2000
	s_nop 0
	global_load_lds_dwordx4 v136, s[64:65]
	s_mov_b32 m0, s46
	s_nop 0
	global_load_lds_dwordx4 v130, s[44:45]
	s_mov_b32 m0, s47
	s_nop 0
	global_load_lds_dwordx4 v134, s[44:45]
	s_waitcnt vmcnt(8)
	s_waitcnt lgkmcnt(0)
	s_barrier
	v_mfma_f32_16x16x32_bf16 v[60:63], v[146:149], v[184:187], v[60:63]
	v_mfma_f32_16x16x32_bf16 v[56:59], v[160:163], v[184:187], v[56:59]
	v_mfma_f32_16x16x32_bf16 v[44:47], v[146:149], v[192:195], v[44:47]
	v_mfma_f32_16x16x32_bf16 v[40:43], v[160:163], v[192:195], v[40:43]
	v_mfma_f32_16x16x32_bf16 v[28:31], v[146:149], v[200:203], v[28:31]
	v_mfma_f32_16x16x32_bf16 v[24:27], v[160:163], v[200:203], v[24:27]
	v_mfma_f32_16x16x32_bf16 v[12:15], v[146:149], v[210:213], v[12:15]
	v_mfma_f32_16x16x32_bf16 v[8:11], v[160:163], v[210:213], v[8:11]
	v_mfma_f32_16x16x32_bf16 v[60:63], v[156:159], v[188:191], v[60:63]
	v_mfma_f32_16x16x32_bf16 v[56:59], v[164:167], v[188:191], v[56:59]
	v_mfma_f32_16x16x32_bf16 v[44:47], v[156:159], v[196:199], v[44:47]
	v_mfma_f32_16x16x32_bf16 v[40:43], v[164:167], v[196:199], v[40:43]
	v_mfma_f32_16x16x32_bf16 v[28:31], v[156:159], v[206:209], v[28:31]
	v_mfma_f32_16x16x32_bf16 v[24:27], v[164:167], v[206:209], v[24:27]
	v_mfma_f32_16x16x32_bf16 v[12:15], v[156:159], v[214:217], v[12:15]
	v_mfma_f32_16x16x32_bf16 v[8:11], v[164:167], v[214:217], v[8:11]
	v_mfma_f32_16x16x32_bf16 v[52:55], v[168:171], v[184:187], v[52:55]
	v_mfma_f32_16x16x32_bf16 v[48:51], v[176:179], v[184:187], v[48:51]
	v_mfma_f32_16x16x32_bf16 v[36:39], v[168:171], v[192:195], v[36:39]
	v_mfma_f32_16x16x32_bf16 v[32:35], v[176:179], v[192:195], v[32:35]
	v_mfma_f32_16x16x32_bf16 v[20:23], v[168:171], v[200:203], v[20:23]
	v_mfma_f32_16x16x32_bf16 v[16:19], v[176:179], v[200:203], v[16:19]
	v_mfma_f32_16x16x32_bf16 v[4:7], v[168:171], v[210:213], v[4:7]
	v_mfma_f32_16x16x32_bf16 v[0:3], v[176:179], v[210:213], v[0:3]
	v_mfma_f32_16x16x32_bf16 v[52:55], v[172:175], v[188:191], v[52:55]
	v_mfma_f32_16x16x32_bf16 v[48:51], v[180:183], v[188:191], v[48:51]
	v_mfma_f32_16x16x32_bf16 v[36:39], v[172:175], v[196:199], v[36:39]
	v_mfma_f32_16x16x32_bf16 v[32:35], v[180:183], v[196:199], v[32:35]
	v_mfma_f32_16x16x32_bf16 v[20:23], v[172:175], v[206:209], v[20:23]
	v_mfma_f32_16x16x32_bf16 v[16:19], v[180:183], v[206:209], v[16:19]
	v_mfma_f32_16x16x32_bf16 v[4:7], v[172:175], v[214:217], v[4:7]
	v_mfma_f32_16x16x32_bf16 v[0:3], v[180:183], v[214:217], v[0:3]
	s_barrier
; #define PG8_STAGE(bufoff, gbase, voff) do { _Pragma("unroll") for (int _i = 0; _i < 2; ++_i) \
;         __builtin_amdgcn_global_load_lds((const unsigned*)((const char*)(gbase) + (voff)[_i]), (PG8_LAS unsigned*)(lds + (bufoff) + ldsw + _i * 8192), 16, 0, 0); } while (0)
; #define PG8_LDA(dst, b, h) do { _Pragma("unroll") for (int m = 0; m < 4; ++m) _Pragma("unroll") for (int k = 0; k < 2; ++k) dst[m][k] = *(const PG8_LAS bf16x8*)(lds + PG8_SA(b, h) + aoff + m * 2048 + k * 1024); } while (0)
; #define PG8_LDB(dst, b, h) do { _Pragma("unroll") for (int n = 0; n < 2; ++n) _Pragma("unroll") for (int k = 0; k < 2; ++k) dst[n][k] = *(const PG8_LAS bf16x8*)(lds + PG8_SB(b, h) + boff + n * 2048 + k * 1024); } while (0)
; #define PG8_MMA(ai, bj, At, Bt) do { __builtin_amdgcn_s_setprio(1); _Pragma("unroll") for (int m = 0; m < 4; ++m) _Pragma("unroll") for (int n = 0; n < 2; ++n) _Pragma("unroll") for (int k = 0; k < 2; ++k) \
;         acc[ai][bj][m][n] = __builtin_amdgcn_mfma_f32_16x16x32_bf16(Bt[n][k], At[m][k], acc[ai][bj][m][n], 0, 0, 0); __builtin_amdgcn_s_setprio(0); } while (0)
; #define PG8_WAIT_V(n) asm volatile("s_waitcnt vmcnt(" #n ")" ::: "memory")
; #define PG8_WAIT_L(n) asm volatile("s_waitcnt lgkmcnt(" #n ")" ::: "memory")
; #define PG8_BAR __builtin_amdgcn_s_barrier()
; #define PG8_SCHED __builtin_amdgcn_sched_barrier(0)
; template <class Epi, class Sched, bool ALIGN_EPI = false, bool SP2 = false>
; __device__ __forceinline__ void gemm_phase(PG8_LAS unsigned char* lds, const Gemm g, const Sched& S, const Epi& E) {
;     ...
;             PG8_LDB(B0, 1, 0); PG8_LDB(B1, 1, 1); PG8_SCHED; PG8_LDA(At, 1, 0); PG8_STAGE(PG8_SA(0, 1), a2 + hstep, voffA);
;             PG8_WAIT_V(8); PG8_WAIT_L(0); PG8_BAR; PG8_MMA(0, 0, At, B0); PG8_MMA(0, 1, At, B1); PG8_BAR; PG8_SCHED;
;             PG8_LDA(At, 1, 1); PG8_STAGE(PG8_SB(1, 0), b3, voffB); PG8_STAGE(PG8_SB(1, 1), b3 + hstep, voffB); PG8_STAGE(PG8_SA(1, 0), a3, voffA);
;             PG8_WAIT_V(8); PG8_WAIT_L(0); PG8_BAR; PG8_MMA(1, 0, At, B0); PG8_MMA(1, 1, At, B1); PG8_BAR; PG8_SCHED;
;     ...
;         }
;         if constexpr (ALIGN_EPI) { if (wr == 0) PG8_BAR; }
	s_add_i32 s63, 0, 0x18000
	s_add_i32 s64, 0, 0x1c000
	ds_read_b128 v[146:149], v240
	ds_read_b128 v[156:159], v240 offset:1024
	ds_read_b128 v[160:163], v240 offset:2048
	ds_read_b128 v[164:167], v240 offset:3072
	ds_read_b128 v[168:171], v241
	ds_read_b128 v[172:175], v241 offset:1024
	ds_read_b128 v[176:179], v241 offset:2048
	ds_read_b128 v[180:183], v241 offset:3072
	s_add_u32 s100, s44, 0x80
	s_addc_u32 s101, s45, 0
	s_add_u32 s44, s44, 0x40000
	s_addc_u32 s45, s45, 0
	s_mov_b32 m0, s48
	ds_read_b128 v[184:187], v153 offset:32768
	ds_read_b128 v[188:191], v153 offset:33792
	ds_read_b128 v[192:195], v153 offset:34816
	ds_read_b128 v[196:199], v153 offset:35840
	ds_read_b128 v[200:203], v153 offset:36864
	ds_read_b128 v[206:209], v153 offset:37888
	ds_read_b128 v[210:213], v153 offset:38912
	ds_read_b128 v[214:217], v153 offset:39936
	global_load_lds_dwordx4 v130, s[44:45]
	s_mov_b32 m0, s49
	s_nop 0
	global_load_lds_dwordx4 v134, s[44:45]
	s_waitcnt vmcnt(8)
	s_waitcnt lgkmcnt(0)
	s_barrier
	v_mfma_f32_16x16x32_bf16 v[124:127], v[146:149], v[184:187], v[124:127]
	v_mfma_f32_16x16x32_bf16 v[120:123], v[160:163], v[184:187], v[120:123]
	v_mfma_f32_16x16x32_bf16 v[108:111], v[146:149], v[192:195], v[108:111]
	v_mfma_f32_16x16x32_bf16 v[104:107], v[160:163], v[192:195], v[104:107]
	v_mfma_f32_16x16x32_bf16 v[92:95], v[146:149], v[200:203], v[92:95]
	v_mfma_f32_16x16x32_bf16 v[88:91], v[160:163], v[200:203], v[88:91]
	v_mfma_f32_16x16x32_bf16 v[76:79], v[146:149], v[210:213], v[76:79]
	v_mfma_f32_16x16x32_bf16 v[72:75], v[160:163], v[210:213], v[72:75]
	v_mfma_f32_16x16x32_bf16 v[124:127], v[156:159], v[188:191], v[124:127]
	v_mfma_f32_16x16x32_bf16 v[120:123], v[164:167], v[188:191], v[120:123]
	v_mfma_f32_16x16x32_bf16 v[108:111], v[156:159], v[196:199], v[108:111]
	v_mfma_f32_16x16x32_bf16 v[104:107], v[164:167], v[196:199], v[104:107]
	v_mfma_f32_16x16x32_bf16 v[92:95], v[156:159], v[206:209], v[92:95]
	v_mfma_f32_16x16x32_bf16 v[88:91], v[164:167], v[206:209], v[88:91]
	v_mfma_f32_16x16x32_bf16 v[76:79], v[156:159], v[214:217], v[76:79]
	v_mfma_f32_16x16x32_bf16 v[72:75], v[164:167], v[214:217], v[72:75]
	v_mfma_f32_16x16x32_bf16 v[116:119], v[168:171], v[184:187], v[116:119]
	v_mfma_f32_16x16x32_bf16 v[112:115], v[176:179], v[184:187], v[112:115]
	v_mfma_f32_16x16x32_bf16 v[100:103], v[168:171], v[192:195], v[100:103]
	v_mfma_f32_16x16x32_bf16 v[96:99], v[176:179], v[192:195], v[96:99]
	v_mfma_f32_16x16x32_bf16 v[84:87], v[168:171], v[200:203], v[84:87]
	v_mfma_f32_16x16x32_bf16 v[80:83], v[176:179], v[200:203], v[80:83]
	v_mfma_f32_16x16x32_bf16 v[68:71], v[168:171], v[210:213], v[68:71]
	v_mfma_f32_16x16x32_bf16 v[64:67], v[176:179], v[210:213], v[64:67]
	v_mfma_f32_16x16x32_bf16 v[116:119], v[172:175], v[188:191], v[116:119]
	v_mfma_f32_16x16x32_bf16 v[112:115], v[180:183], v[188:191], v[112:115]
	v_mfma_f32_16x16x32_bf16 v[100:103], v[172:175], v[196:199], v[100:103]
	v_mfma_f32_16x16x32_bf16 v[96:99], v[180:183], v[196:199], v[96:99]
	v_mfma_f32_16x16x32_bf16 v[84:87], v[172:175], v[206:209], v[84:87]
	v_mfma_f32_16x16x32_bf16 v[80:83], v[180:183], v[206:209], v[80:83]
	v_mfma_f32_16x16x32_bf16 v[68:71], v[172:175], v[214:217], v[68:71]
	v_mfma_f32_16x16x32_bf16 v[64:67], v[180:183], v[214:217], v[64:67]
	s_barrier
	s_add_i32 s44, s63, s33
	s_mov_b32 m0, s44
	ds_read_b128 v[184:187], v153 offset:49152
	ds_read_b128 v[188:191], v153 offset:50176
	ds_read_b128 v[192:195], v153 offset:51200
	ds_read_b128 v[196:199], v153 offset:52224
	ds_read_b128 v[200:203], v153 offset:53248
	ds_read_b128 v[206:209], v153 offset:54272
	ds_read_b128 v[210:213], v153 offset:55296
	ds_read_b128 v[214:217], v153 offset:56320
	global_load_lds_dwordx4 v132, s[98:99]
	s_add_i32 m0, s44, 0x2000
	s_add_u32 s42, s42, 0x40080
	s_addc_u32 s43, s43, 0
	s_add_i32 s44, s64, s33
	global_load_lds_dwordx4 v136, s[98:99]
	s_mov_b32 m0, s44
	s_nop 0
	global_load_lds_dwordx4 v132, s[42:43]
	s_add_i32 m0, s44, 0x2000
	s_nop 0
	global_load_lds_dwordx4 v136, s[42:43]
	s_mov_b32 m0, s52
	s_nop 0
	global_load_lds_dwordx4 v130, s[100:101]
	s_mov_b32 m0, s53
	s_nop 0
	global_load_lds_dwordx4 v134, s[100:101]
	s_waitcnt vmcnt(8)
	s_waitcnt lgkmcnt(0)
	s_barrier
	v_mfma_f32_16x16x32_bf16 v[60:63], v[146:149], v[184:187], v[60:63]
	v_mfma_f32_16x16x32_bf16 v[56:59], v[160:163], v[184:187], v[56:59]
	v_mfma_f32_16x16x32_bf16 v[44:47], v[146:149], v[192:195], v[44:47]
	v_mfma_f32_16x16x32_bf16 v[40:43], v[160:163], v[192:195], v[40:43]
	v_mfma_f32_16x16x32_bf16 v[28:31], v[146:149], v[200:203], v[28:31]
	v_mfma_f32_16x16x32_bf16 v[24:27], v[160:163], v[200:203], v[24:27]
	v_mfma_f32_16x16x32_bf16 v[12:15], v[146:149], v[210:213], v[12:15]
	v_mfma_f32_16x16x32_bf16 v[8:11], v[160:163], v[210:213], v[8:11]
	v_mfma_f32_16x16x32_bf16 v[60:63], v[156:159], v[188:191], v[60:63]
	v_mfma_f32_16x16x32_bf16 v[56:59], v[164:167], v[188:191], v[56:59]
	v_mfma_f32_16x16x32_bf16 v[44:47], v[156:159], v[196:199], v[44:47]
	v_mfma_f32_16x16x32_bf16 v[40:43], v[164:167], v[196:199], v[40:43]
	v_mfma_f32_16x16x32_bf16 v[28:31], v[156:159], v[206:209], v[28:31]
	v_mfma_f32_16x16x32_bf16 v[24:27], v[164:167], v[206:209], v[24:27]
	v_mfma_f32_16x16x32_bf16 v[12:15], v[156:159], v[214:217], v[12:15]
	v_mfma_f32_16x16x32_bf16 v[8:11], v[164:167], v[214:217], v[8:11]
	v_mfma_f32_16x16x32_bf16 v[52:55], v[168:171], v[184:187], v[52:55]
	v_mfma_f32_16x16x32_bf16 v[48:51], v[176:179], v[184:187], v[48:51]
	v_mfma_f32_16x16x32_bf16 v[36:39], v[168:171], v[192:195], v[36:39]
	v_mfma_f32_16x16x32_bf16 v[32:35], v[176:179], v[192:195], v[32:35]
	v_mfma_f32_16x16x32_bf16 v[20:23], v[168:171], v[200:203], v[20:23]
	v_mfma_f32_16x16x32_bf16 v[16:19], v[176:179], v[200:203], v[16:19]
	v_mfma_f32_16x16x32_bf16 v[4:7], v[168:171], v[210:213], v[4:7]
	v_mfma_f32_16x16x32_bf16 v[0:3], v[176:179], v[210:213], v[0:3]
	v_mfma_f32_16x16x32_bf16 v[52:55], v[172:175], v[188:191], v[52:55]
	v_mfma_f32_16x16x32_bf16 v[48:51], v[180:183], v[188:191], v[48:51]
	v_mfma_f32_16x16x32_bf16 v[36:39], v[172:175], v[196:199], v[36:39]
	v_mfma_f32_16x16x32_bf16 v[32:35], v[180:183], v[196:199], v[32:35]
	v_mfma_f32_16x16x32_bf16 v[20:23], v[172:175], v[206:209], v[20:23]
	v_mfma_f32_16x16x32_bf16 v[16:19], v[180:183], v[206:209], v[16:19]
	v_mfma_f32_16x16x32_bf16 v[4:7], v[172:175], v[214:217], v[4:7]
	v_mfma_f32_16x16x32_bf16 v[0:3], v[180:183], v[214:217], v[0:3]
	s_barrier
	s_add_i32 s62, s62, 2
	s_add_u32 s40, s40, 0x100
	s_addc_u32 s41, s41, 0
	s_add_u32 s60, s60, 0x100
	s_addc_u32 s61, s61, 0
	s_cmp_gt_u32 s62, 13
	s_cbranch_scc0 .LBB0_905
	s_and_b64 vcc, exec, s[28:29]
	s_cbranch_vccz .LBB0_908
	s_barrier

; #define PG8_STAGE(bufoff, gbase, voff) do { _Pragma("unroll") for (int _i = 0; _i < 2; ++_i) \
;         __builtin_amdgcn_global_load_lds((const unsigned*)((const char*)(gbase) + (voff)[_i]), (PG8_LAS unsigned*)(lds + (bufoff) + ldsw + _i * 8192), 16, 0, 0); } while (0)
; #define PG8_LDA(dst, b, h) do { _Pragma("unroll") for (int m = 0; m < 4; ++m) _Pragma("unroll") for (int k = 0; k < 2; ++k) dst[m][k] = *(const PG8_LAS bf16x8*)(lds + PG8_SA(b, h) + aoff + m * 2048 + k * 1024); } while (0)
; #define PG8_LDB(dst, b, h) do { _Pragma("unroll") for (int n = 0; n < 2; ++n) _Pragma("unroll") for (int k = 0; k < 2; ++k) dst[n][k] = *(const PG8_LAS bf16x8*)(lds + PG8_SB(b, h) + boff + n * 2048 + k * 1024); } while (0)
; #define PG8_MMA(ai, bj, At, Bt) do { __builtin_amdgcn_s_setprio(1); _Pragma("unroll") for (int m = 0; m < 4; ++m) _Pragma("unroll") for (int n = 0; n < 2; ++n) _Pragma("unroll") for (int k = 0; k < 2; ++k) \
;         acc[ai][bj][m][n] = __builtin_amdgcn_mfma_f32_16x16x32_bf16(Bt[n][k], At[m][k], acc[ai][bj][m][n], 0, 0, 0); __builtin_amdgcn_s_setprio(0); } while (0)
; #define PG8_WAIT_V(n) asm volatile("s_waitcnt vmcnt(" #n ")" ::: "memory")
; #define PG8_WAIT_L(n) asm volatile("s_waitcnt lgkmcnt(" #n ")" ::: "memory")
; #define PG8_BAR __builtin_amdgcn_s_barrier()
; #define PG8_SCHED __builtin_amdgcn_sched_barrier(0)
; template <class Epi, class Sched, bool ALIGN_EPI = false, bool SP2 = false>
; __device__ __forceinline__ void gemm_phase(PG8_LAS unsigned char* lds, const Gemm g, const Sched& S, const Epi& E) {
;     ...
;             PG8_LDB(B0, 0, 0); PG8_LDB(B1, 0, 1); PG8_SCHED; PG8_LDA(At, 0, 0); PG8_STAGE(PG8_SA(1, 1), a1 + hstep, voffA);
;             PG8_WAIT_V(8); PG8_WAIT_L(0); PG8_BAR; PG8_MMA(0, 0, At, B0); PG8_MMA(0, 1, At, B1); PG8_BAR; PG8_SCHED;
;             PG8_LDA(At, 0, 1); PG8_STAGE(PG8_SB(0, 0), b2, voffB); PG8_STAGE(PG8_SB(0, 1), b2 + hstep, voffB); PG8_STAGE(PG8_SA(0, 0), a2, voffA);
;             PG8_WAIT_V(8); PG8_WAIT_L(0); PG8_BAR; PG8_MMA(1, 0, At, B0); PG8_MMA(1, 1, At, B1); PG8_BAR; PG8_SCHED;
.LBB0_1001:
	ds_read_b128 v[146:149], v152
	ds_read_b128 v[156:159], v152 offset:1024
	ds_read_b128 v[160:163], v152 offset:2048
	ds_read_b128 v[164:167], v152 offset:3072
	ds_read_b128 v[168:171], v153
	ds_read_b128 v[172:175], v153 offset:1024
	ds_read_b128 v[176:179], v153 offset:2048
	ds_read_b128 v[180:183], v153 offset:3072
	s_add_u32 s30, s28, 0xfff00080
	s_addc_u32 s31, s29, -1
	s_cmp_eq_u32 s51, 60
	s_cselect_b32 s35, s21, s31
	s_cselect_b32 s34, s47, s30
	s_cselect_b32 s31, s19, s50
	s_cselect_b32 s30, s48, s49
	s_add_i32 m0, s27, 0xc000
	ds_read_b128 v[184:187], v154
	ds_read_b128 v[188:191], v154 offset:1024
	ds_read_b128 v[192:195], v154 offset:2048
	ds_read_b128 v[196:199], v154 offset:3072
	ds_read_b128 v[200:203], v154 offset:4096
	ds_read_b128 v[206:209], v154 offset:5120
	ds_read_b128 v[210:213], v154 offset:6144
	ds_read_b128 v[214:217], v154 offset:7168
	global_load_lds_dwordx4 v138, s[28:29]
	s_add_i32 m0, s27, 0xe000
	s_nop 0
	global_load_lds_dwordx4 v140, s[28:29]
	s_waitcnt vmcnt(8)
	s_waitcnt lgkmcnt(0)
	s_barrier
	v_mfma_f32_16x16x32_bf16 v[124:127], v[146:149], v[184:187], v[124:127]
	v_mfma_f32_16x16x32_bf16 v[120:123], v[160:163], v[184:187], v[120:123]
	v_mfma_f32_16x16x32_bf16 v[108:111], v[146:149], v[192:195], v[108:111]
	v_mfma_f32_16x16x32_bf16 v[104:107], v[160:163], v[192:195], v[104:107]
	v_mfma_f32_16x16x32_bf16 v[92:95], v[146:149], v[200:203], v[92:95]
	v_mfma_f32_16x16x32_bf16 v[88:91], v[160:163], v[200:203], v[88:91]
	v_mfma_f32_16x16x32_bf16 v[76:79], v[146:149], v[210:213], v[76:79]
	v_mfma_f32_16x16x32_bf16 v[72:75], v[160:163], v[210:213], v[72:75]
	v_mfma_f32_16x16x32_bf16 v[124:127], v[156:159], v[188:191], v[124:127]
	v_mfma_f32_16x16x32_bf16 v[120:123], v[164:167], v[188:191], v[120:123]
	v_mfma_f32_16x16x32_bf16 v[108:111], v[156:159], v[196:199], v[108:111]
	v_mfma_f32_16x16x32_bf16 v[104:107], v[164:167], v[196:199], v[104:107]
	v_mfma_f32_16x16x32_bf16 v[92:95], v[156:159], v[206:209], v[92:95]
	v_mfma_f32_16x16x32_bf16 v[88:91], v[164:167], v[206:209], v[88:91]
	v_mfma_f32_16x16x32_bf16 v[76:79], v[156:159], v[214:217], v[76:79]
	v_mfma_f32_16x16x32_bf16 v[72:75], v[164:167], v[214:217], v[72:75]
	v_mfma_f32_16x16x32_bf16 v[116:119], v[168:171], v[184:187], v[116:119]
	v_mfma_f32_16x16x32_bf16 v[112:115], v[176:179], v[184:187], v[112:115]
	v_mfma_f32_16x16x32_bf16 v[100:103], v[168:171], v[192:195], v[100:103]
	v_mfma_f32_16x16x32_bf16 v[96:99], v[176:179], v[192:195], v[96:99]
	v_mfma_f32_16x16x32_bf16 v[84:87], v[168:171], v[200:203], v[84:87]
	v_mfma_f32_16x16x32_bf16 v[80:83], v[176:179], v[200:203], v[80:83]
	v_mfma_f32_16x16x32_bf16 v[68:71], v[168:171], v[210:213], v[68:71]
	v_mfma_f32_16x16x32_bf16 v[64:67], v[176:179], v[210:213], v[64:67]
	v_mfma_f32_16x16x32_bf16 v[116:119], v[172:175], v[188:191], v[116:119]
	v_mfma_f32_16x16x32_bf16 v[112:115], v[180:183], v[188:191], v[112:115]
	v_mfma_f32_16x16x32_bf16 v[100:103], v[172:175], v[196:199], v[100:103]
	v_mfma_f32_16x16x32_bf16 v[96:99], v[180:183], v[196:199], v[96:99]
	v_mfma_f32_16x16x32_bf16 v[84:87], v[172:175], v[206:209], v[84:87]
	v_mfma_f32_16x16x32_bf16 v[80:83], v[180:183], v[206:209], v[80:83]
	v_mfma_f32_16x16x32_bf16 v[68:71], v[172:175], v[214:217], v[68:71]
	v_mfma_f32_16x16x32_bf16 v[64:67], v[180:183], v[214:217], v[64:67]
	s_barrier
	s_add_i32 s52, s44, s33
	s_mov_b32 m0, s52
	ds_read_b128 v[184:187], v154 offset:16384
	ds_read_b128 v[188:191], v154 offset:17408
	ds_read_b128 v[192:195], v154 offset:18432
	ds_read_b128 v[196:199], v154 offset:19456
	ds_read_b128 v[200:203], v154 offset:20480
	ds_read_b128 v[206:209], v154 offset:21504
	ds_read_b128 v[210:213], v154 offset:22528
	ds_read_b128 v[214:217], v154 offset:23552
	global_load_lds_dwordx4 v132, s[30:31]
	s_add_i32 m0, s52, 0x2000
	s_add_u32 s98, s30, 0x80
	s_addc_u32 s99, s31, 0
	s_add_u32 s52, s30, 0x100000
	s_addc_u32 s53, s31, 0
	s_add_i32 s54, s45, s33
	global_load_lds_dwordx4 v136, s[30:31]
	s_mov_b32 m0, s54
	s_nop 0
	global_load_lds_dwordx4 v132, s[52:53]
	s_add_i32 m0, s54, 0x2000
	s_nop 0
	global_load_lds_dwordx4 v136, s[52:53]
	s_mov_b32 m0, s27
	s_nop 0
	global_load_lds_dwordx4 v130, s[34:35]
	s_mov_b32 m0, s36
	s_nop 0
	global_load_lds_dwordx4 v134, s[34:35]
	s_waitcnt vmcnt(8)
	s_waitcnt lgkmcnt(0)
	s_barrier
	v_mfma_f32_16x16x32_bf16 v[60:63], v[146:149], v[184:187], v[60:63]
	v_mfma_f32_16x16x32_bf16 v[56:59], v[160:163], v[184:187], v[56:59]
	v_mfma_f32_16x16x32_bf16 v[44:47], v[146:149], v[192:195], v[44:47]
	v_mfma_f32_16x16x32_bf16 v[40:43], v[160:163], v[192:195], v[40:43]
	v_mfma_f32_16x16x32_bf16 v[28:31], v[146:149], v[200:203], v[28:31]
	v_mfma_f32_16x16x32_bf16 v[24:27], v[160:163], v[200:203], v[24:27]
	v_mfma_f32_16x16x32_bf16 v[12:15], v[146:149], v[210:213], v[12:15]
	v_mfma_f32_16x16x32_bf16 v[8:11], v[160:163], v[210:213], v[8:11]
	v_mfma_f32_16x16x32_bf16 v[60:63], v[156:159], v[188:191], v[60:63]
	v_mfma_f32_16x16x32_bf16 v[56:59], v[164:167], v[188:191], v[56:59]
	v_mfma_f32_16x16x32_bf16 v[44:47], v[156:159], v[196:199], v[44:47]
	v_mfma_f32_16x16x32_bf16 v[40:43], v[164:167], v[196:199], v[40:43]
	v_mfma_f32_16x16x32_bf16 v[28:31], v[156:159], v[206:209], v[28:31]
	v_mfma_f32_16x16x32_bf16 v[24:27], v[164:167], v[206:209], v[24:27]
	v_mfma_f32_16x16x32_bf16 v[12:15], v[156:159], v[214:217], v[12:15]
	v_mfma_f32_16x16x32_bf16 v[8:11], v[164:167], v[214:217], v[8:11]
	v_mfma_f32_16x16x32_bf16 v[52:55], v[168:171], v[184:187], v[52:55]
	v_mfma_f32_16x16x32_bf16 v[48:51], v[176:179], v[184:187], v[48:51]
	v_mfma_f32_16x16x32_bf16 v[36:39], v[168:171], v[192:195], v[36:39]
	v_mfma_f32_16x16x32_bf16 v[32:35], v[176:179], v[192:195], v[32:35]
	v_mfma_f32_16x16x32_bf16 v[20:23], v[168:171], v[200:203], v[20:23]
	v_mfma_f32_16x16x32_bf16 v[16:19], v[176:179], v[200:203], v[16:19]
	v_mfma_f32_16x16x32_bf16 v[4:7], v[168:171], v[210:213], v[4:7]
	v_mfma_f32_16x16x32_bf16 v[0:3], v[176:179], v[210:213], v[0:3]
	v_mfma_f32_16x16x32_bf16 v[52:55], v[172:175], v[188:191], v[52:55]
	v_mfma_f32_16x16x32_bf16 v[48:51], v[180:183], v[188:191], v[48:51]
	v_mfma_f32_16x16x32_bf16 v[36:39], v[172:175], v[196:199], v[36:39]
	v_mfma_f32_16x16x32_bf16 v[32:35], v[180:183], v[196:199], v[32:35]
	v_mfma_f32_16x16x32_bf16 v[20:23], v[172:175], v[206:209], v[20:23]
	v_mfma_f32_16x16x32_bf16 v[16:19], v[180:183], v[206:209], v[16:19]
	v_mfma_f32_16x16x32_bf16 v[4:7], v[172:175], v[214:217], v[4:7]
	v_mfma_f32_16x16x32_bf16 v[0:3], v[180:183], v[214:217], v[0:3]
	s_barrier
; #define PG8_STAGE(bufoff, gbase, voff) do { _Pragma("unroll") for (int _i = 0; _i < 2; ++_i) \
;         __builtin_amdgcn_global_load_lds((const unsigned*)((const char*)(gbase) + (voff)[_i]), (PG8_LAS unsigned*)(lds + (bufoff) + ldsw + _i * 8192), 16, 0, 0); } while (0)
; #define PG8_LDA(dst, b, h) do { _Pragma("unroll") for (int m = 0; m < 4; ++m) _Pragma("unroll") for (int k = 0; k < 2; ++k) dst[m][k] = *(const PG8_LAS bf16x8*)(lds + PG8_SA(b, h) + aoff + m * 2048 + k * 1024); } while (0)
; #define PG8_LDB(dst, b, h) do { _Pragma("unroll") for (int n = 0; n < 2; ++n) _Pragma("unroll") for (int k = 0; k < 2; ++k) dst[n][k] = *(const PG8_LAS bf16x8*)(lds + PG8_SB(b, h) + boff + n * 2048 + k * 1024); } while (0)
; #define PG8_MMA(ai, bj, At, Bt) do { __builtin_amdgcn_s_setprio(1); _Pragma("unroll") for (int m = 0; m < 4; ++m) _Pragma("unroll") for (int n = 0; n < 2; ++n) _Pragma("unroll") for (int k = 0; k < 2; ++k) \
;         acc[ai][bj][m][n] = __builtin_amdgcn_mfma_f32_16x16x32_bf16(Bt[n][k], At[m][k], acc[ai][bj][m][n], 0, 0, 0); __builtin_amdgcn_s_setprio(0); } while (0)
; #define PG8_WAIT_V(n) asm volatile("s_waitcnt vmcnt(" #n ")" ::: "memory")
; #define PG8_WAIT_L(n) asm volatile("s_waitcnt lgkmcnt(" #n ")" ::: "memory")
; #define PG8_BAR __builtin_amdgcn_s_barrier()
; #define PG8_SCHED __builtin_amdgcn_sched_barrier(0)
; template <class Epi, class Sched, bool ALIGN_EPI = false, bool SP2 = false>
; __device__ __forceinline__ void gemm_phase(PG8_LAS unsigned char* lds, const Gemm g, const Sched& S, const Epi& E) {
;     ...
;             PG8_LDB(B0, 1, 0); PG8_LDB(B1, 1, 1); PG8_SCHED; PG8_LDA(At, 1, 0); PG8_STAGE(PG8_SA(0, 1), a2 + hstep, voffA);
;             PG8_WAIT_V(8); PG8_WAIT_L(0); PG8_BAR; PG8_MMA(0, 0, At, B0); PG8_MMA(0, 1, At, B1); PG8_BAR; PG8_SCHED;
;             PG8_LDA(At, 1, 1); PG8_STAGE(PG8_SB(1, 0), b3, voffB); PG8_STAGE(PG8_SB(1, 1), b3 + hstep, voffB); PG8_STAGE(PG8_SA(1, 0), a3, voffA);
;             PG8_WAIT_V(8); PG8_WAIT_L(0); PG8_BAR; PG8_MMA(1, 0, At, B0); PG8_MMA(1, 1, At, B1); PG8_BAR; PG8_SCHED;
;     ...
;         }
;         if constexpr (ALIGN_EPI) { if (wr == 0) PG8_BAR; }
	s_add_i32 s52, 0, 0x18000
	s_add_i32 s53, 0, 0x1c000
	ds_read_b128 v[146:149], v240
	ds_read_b128 v[156:159], v240 offset:1024
	ds_read_b128 v[160:163], v240 offset:2048
	ds_read_b128 v[164:167], v240 offset:3072
	ds_read_b128 v[168:171], v241
	ds_read_b128 v[172:175], v241 offset:1024
	ds_read_b128 v[176:179], v241 offset:2048
	ds_read_b128 v[180:183], v241 offset:3072
	s_add_u32 s100, s34, 0x80
	s_addc_u32 s101, s35, 0
	s_add_u32 s34, s34, 0x100000
	s_addc_u32 s35, s35, 0
	s_mov_b32 m0, s37
	ds_read_b128 v[184:187], v154 offset:32768
	ds_read_b128 v[188:191], v154 offset:33792
	ds_read_b128 v[192:195], v154 offset:34816
	ds_read_b128 v[196:199], v154 offset:35840
	ds_read_b128 v[200:203], v154 offset:36864
	ds_read_b128 v[206:209], v154 offset:37888
	ds_read_b128 v[210:213], v154 offset:38912
	ds_read_b128 v[214:217], v154 offset:39936
	global_load_lds_dwordx4 v130, s[34:35]
	s_mov_b32 m0, s38
	s_nop 0
	global_load_lds_dwordx4 v134, s[34:35]
	s_waitcnt vmcnt(8)
	s_waitcnt lgkmcnt(0)
	s_barrier
	v_mfma_f32_16x16x32_bf16 v[124:127], v[146:149], v[184:187], v[124:127]
	v_mfma_f32_16x16x32_bf16 v[120:123], v[160:163], v[184:187], v[120:123]
	v_mfma_f32_16x16x32_bf16 v[108:111], v[146:149], v[192:195], v[108:111]
	v_mfma_f32_16x16x32_bf16 v[104:107], v[160:163], v[192:195], v[104:107]
	v_mfma_f32_16x16x32_bf16 v[92:95], v[146:149], v[200:203], v[92:95]
	v_mfma_f32_16x16x32_bf16 v[88:91], v[160:163], v[200:203], v[88:91]
	v_mfma_f32_16x16x32_bf16 v[76:79], v[146:149], v[210:213], v[76:79]
	v_mfma_f32_16x16x32_bf16 v[72:75], v[160:163], v[210:213], v[72:75]
	v_mfma_f32_16x16x32_bf16 v[124:127], v[156:159], v[188:191], v[124:127]
	v_mfma_f32_16x16x32_bf16 v[120:123], v[164:167], v[188:191], v[120:123]
	v_mfma_f32_16x16x32_bf16 v[108:111], v[156:159], v[196:199], v[108:111]
	v_mfma_f32_16x16x32_bf16 v[104:107], v[164:167], v[196:199], v[104:107]
	v_mfma_f32_16x16x32_bf16 v[92:95], v[156:159], v[206:209], v[92:95]
	v_mfma_f32_16x16x32_bf16 v[88:91], v[164:167], v[206:209], v[88:91]
	v_mfma_f32_16x16x32_bf16 v[76:79], v[156:159], v[214:217], v[76:79]
	v_mfma_f32_16x16x32_bf16 v[72:75], v[164:167], v[214:217], v[72:75]
	v_mfma_f32_16x16x32_bf16 v[116:119], v[168:171], v[184:187], v[116:119]
	v_mfma_f32_16x16x32_bf16 v[112:115], v[176:179], v[184:187], v[112:115]
	v_mfma_f32_16x16x32_bf16 v[100:103], v[168:171], v[192:195], v[100:103]
	v_mfma_f32_16x16x32_bf16 v[96:99], v[176:179], v[192:195], v[96:99]
	v_mfma_f32_16x16x32_bf16 v[84:87], v[168:171], v[200:203], v[84:87]
	v_mfma_f32_16x16x32_bf16 v[80:83], v[176:179], v[200:203], v[80:83]
	v_mfma_f32_16x16x32_bf16 v[68:71], v[168:171], v[210:213], v[68:71]
	v_mfma_f32_16x16x32_bf16 v[64:67], v[176:179], v[210:213], v[64:67]
	v_mfma_f32_16x16x32_bf16 v[116:119], v[172:175], v[188:191], v[116:119]
	v_mfma_f32_16x16x32_bf16 v[112:115], v[180:183], v[188:191], v[112:115]
	v_mfma_f32_16x16x32_bf16 v[100:103], v[172:175], v[196:199], v[100:103]
	v_mfma_f32_16x16x32_bf16 v[96:99], v[180:183], v[196:199], v[96:99]
	v_mfma_f32_16x16x32_bf16 v[84:87], v[172:175], v[206:209], v[84:87]
	v_mfma_f32_16x16x32_bf16 v[80:83], v[180:183], v[206:209], v[80:83]
	v_mfma_f32_16x16x32_bf16 v[68:71], v[172:175], v[214:217], v[68:71]
	v_mfma_f32_16x16x32_bf16 v[64:67], v[180:183], v[214:217], v[64:67]
	s_barrier
	s_add_i32 s34, s52, s33
	s_mov_b32 m0, s34
	ds_read_b128 v[184:187], v154 offset:49152
	ds_read_b128 v[188:191], v154 offset:50176
	ds_read_b128 v[192:195], v154 offset:51200
	ds_read_b128 v[196:199], v154 offset:52224
	ds_read_b128 v[200:203], v154 offset:53248
	ds_read_b128 v[206:209], v154 offset:54272
	ds_read_b128 v[210:213], v154 offset:55296
	ds_read_b128 v[214:217], v154 offset:56320
	global_load_lds_dwordx4 v132, s[98:99]
	s_add_i32 m0, s34, 0x2000
	s_add_u32 s30, s30, 0x100080
	s_addc_u32 s31, s31, 0
	s_add_i32 s34, s53, s33
	global_load_lds_dwordx4 v136, s[98:99]
	s_mov_b32 m0, s34
	s_nop 0
	global_load_lds_dwordx4 v132, s[30:31]
	s_add_i32 m0, s34, 0x2000
	s_nop 0
	global_load_lds_dwordx4 v136, s[30:31]
	s_mov_b32 m0, s40
	s_nop 0
	global_load_lds_dwordx4 v130, s[100:101]
	s_mov_b32 m0, s41
	s_nop 0
	global_load_lds_dwordx4 v134, s[100:101]
	s_waitcnt vmcnt(8)
	s_waitcnt lgkmcnt(0)
	s_barrier
	v_mfma_f32_16x16x32_bf16 v[60:63], v[146:149], v[184:187], v[60:63]
	v_mfma_f32_16x16x32_bf16 v[56:59], v[160:163], v[184:187], v[56:59]
	v_mfma_f32_16x16x32_bf16 v[44:47], v[146:149], v[192:195], v[44:47]
	v_mfma_f32_16x16x32_bf16 v[40:43], v[160:163], v[192:195], v[40:43]
	v_mfma_f32_16x16x32_bf16 v[28:31], v[146:149], v[200:203], v[28:31]
	v_mfma_f32_16x16x32_bf16 v[24:27], v[160:163], v[200:203], v[24:27]
	v_mfma_f32_16x16x32_bf16 v[12:15], v[146:149], v[210:213], v[12:15]
	v_mfma_f32_16x16x32_bf16 v[8:11], v[160:163], v[210:213], v[8:11]
	v_mfma_f32_16x16x32_bf16 v[60:63], v[156:159], v[188:191], v[60:63]
	v_mfma_f32_16x16x32_bf16 v[56:59], v[164:167], v[188:191], v[56:59]
	v_mfma_f32_16x16x32_bf16 v[44:47], v[156:159], v[196:199], v[44:47]
	v_mfma_f32_16x16x32_bf16 v[40:43], v[164:167], v[196:199], v[40:43]
	v_mfma_f32_16x16x32_bf16 v[28:31], v[156:159], v[206:209], v[28:31]
	v_mfma_f32_16x16x32_bf16 v[24:27], v[164:167], v[206:209], v[24:27]
	v_mfma_f32_16x16x32_bf16 v[12:15], v[156:159], v[214:217], v[12:15]
	v_mfma_f32_16x16x32_bf16 v[8:11], v[164:167], v[214:217], v[8:11]
	v_mfma_f32_16x16x32_bf16 v[52:55], v[168:171], v[184:187], v[52:55]
	v_mfma_f32_16x16x32_bf16 v[48:51], v[176:179], v[184:187], v[48:51]
	v_mfma_f32_16x16x32_bf16 v[36:39], v[168:171], v[192:195], v[36:39]
	v_mfma_f32_16x16x32_bf16 v[32:35], v[176:179], v[192:195], v[32:35]
	v_mfma_f32_16x16x32_bf16 v[20:23], v[168:171], v[200:203], v[20:23]
	v_mfma_f32_16x16x32_bf16 v[16:19], v[176:179], v[200:203], v[16:19]
	v_mfma_f32_16x16x32_bf16 v[4:7], v[168:171], v[210:213], v[4:7]
	v_mfma_f32_16x16x32_bf16 v[0:3], v[176:179], v[210:213], v[0:3]
	v_mfma_f32_16x16x32_bf16 v[52:55], v[172:175], v[188:191], v[52:55]
	v_mfma_f32_16x16x32_bf16 v[48:51], v[180:183], v[188:191], v[48:51]
	v_mfma_f32_16x16x32_bf16 v[36:39], v[172:175], v[196:199], v[36:39]
	v_mfma_f32_16x16x32_bf16 v[32:35], v[180:183], v[196:199], v[32:35]
	v_mfma_f32_16x16x32_bf16 v[20:23], v[172:175], v[206:209], v[20:23]
	v_mfma_f32_16x16x32_bf16 v[16:19], v[180:183], v[206:209], v[16:19]
	v_mfma_f32_16x16x32_bf16 v[4:7], v[172:175], v[214:217], v[4:7]
	v_mfma_f32_16x16x32_bf16 v[0:3], v[180:183], v[214:217], v[0:3]
	s_barrier
	s_add_i32 s51, s51, 2
	s_add_u32 s28, s28, 0x100
	s_addc_u32 s29, s29, 0
	s_add_u32 s49, s49, 0x100
	s_addc_u32 s50, s50, 0
	s_cmp_gt_u32 s51, 61
	s_cbranch_scc0 .LBB0_1001
	s_and_b64 vcc, exec, s[14:15]
	s_cbranch_vccz .LBB0_1004
	s_barrier

; #define PG8_STAGE(bufoff, gbase, voff) do { _Pragma("unroll") for (int _i = 0; _i < 2; ++_i) \
;         __builtin_amdgcn_global_load_lds((const unsigned*)((const char*)(gbase) + (voff)[_i]), (PG8_LAS unsigned*)(lds + (bufoff) + ldsw + _i * 8192), 16, 0, 0); } while (0)
; #define PG8_LDA(dst, b, h) do { _Pragma("unroll") for (int m = 0; m < 4; ++m) _Pragma("unroll") for (int k = 0; k < 2; ++k) dst[m][k] = *(const PG8_LAS bf16x8*)(lds + PG8_SA(b, h) + aoff + m * 2048 + k * 1024); } while (0)
; #define PG8_LDB(dst, b, h) do { _Pragma("unroll") for (int n = 0; n < 2; ++n) _Pragma("unroll") for (int k = 0; k < 2; ++k) dst[n][k] = *(const PG8_LAS bf16x8*)(lds + PG8_SB(b, h) + boff + n * 2048 + k * 1024); } while (0)
; #define PG8_MMA(ai, bj, At, Bt) do { __builtin_amdgcn_s_setprio(1); _Pragma("unroll") for (int m = 0; m < 4; ++m) _Pragma("unroll") for (int n = 0; n < 2; ++n) _Pragma("unroll") for (int k = 0; k < 2; ++k) \
;         acc[ai][bj][m][n] = __builtin_amdgcn_mfma_f32_16x16x32_bf16(Bt[n][k], At[m][k], acc[ai][bj][m][n], 0, 0, 0); __builtin_amdgcn_s_setprio(0); } while (0)
; #define PG8_WAIT_V(n) asm volatile("s_waitcnt vmcnt(" #n ")" ::: "memory")
; #define PG8_WAIT_L(n) asm volatile("s_waitcnt lgkmcnt(" #n ")" ::: "memory")
; #define PG8_BAR __builtin_amdgcn_s_barrier()
; #define PG8_SCHED __builtin_amdgcn_sched_barrier(0)
; template <class Epi, class Sched, bool ALIGN_EPI = false, bool SP2 = false>
; __device__ __forceinline__ void gemm_phase(PG8_LAS unsigned char* lds, const Gemm g, const Sched& S, const Epi& E) {
;     ...
;             PG8_LDB(B0, 0, 0); PG8_LDB(B1, 0, 1); PG8_SCHED; PG8_LDA(At, 0, 0); PG8_STAGE(PG8_SA(1, 1), a1 + hstep, voffA);
;             PG8_WAIT_V(8); PG8_WAIT_L(0); PG8_BAR; PG8_MMA(0, 0, At, B0); PG8_MMA(0, 1, At, B1); PG8_BAR; PG8_SCHED;
;             PG8_LDA(At, 0, 1); PG8_STAGE(PG8_SB(0, 0), b2, voffB); PG8_STAGE(PG8_SB(0, 1), b2 + hstep, voffB); PG8_STAGE(PG8_SA(0, 0), a2, voffA);
;             PG8_WAIT_V(8); PG8_WAIT_L(0); PG8_BAR; PG8_MMA(1, 0, At, B0); PG8_MMA(1, 1, At, B1); PG8_BAR; PG8_SCHED;
.LBB0_1025:
	s_add_u32 s98, s12, s28
	s_addc_u32 s99, s13, s29
	s_add_u32 s30, s12, s28
	ds_read_b128 v[148:151], v240
	ds_read_b128 v[152:155], v240 offset:1024
	ds_read_b128 v[156:159], v240 offset:2048
	ds_read_b128 v[160:163], v240 offset:3072
	ds_read_b128 v[164:167], v241
	ds_read_b128 v[168:171], v241 offset:1024
	ds_read_b128 v[172:175], v241 offset:2048
	ds_read_b128 v[176:179], v241 offset:3072
	s_addc_u32 s31, s13, s29
	s_add_u32 s30, s30, 0x100
	s_addc_u32 s31, s31, 0
	s_add_u32 s52, s25, s28
	s_addc_u32 s53, s48, s29
	s_cmpk_eq_i32 s28, 0x1f00
	s_cselect_b32 s35, s21, s31
	s_cselect_b32 s34, s49, s30
	s_cselect_b32 s31, s19, s53
	s_cselect_b32 s30, s50, s52
	s_add_i32 m0, s11, 0xc000
	ds_read_b128 v[180:183], v147
	ds_read_b128 v[184:187], v147 offset:1024
	ds_read_b128 v[188:191], v147 offset:2048
	ds_read_b128 v[192:195], v147 offset:3072
	ds_read_b128 v[196:199], v147 offset:4096
	ds_read_b128 v[200:203], v147 offset:5120
	ds_read_b128 v[206:209], v147 offset:6144
	ds_read_b128 v[210:213], v147 offset:7168
	global_load_lds_dwordx4 v128, s[98:99]
	s_add_i32 m0, s11, 0xe000
	s_nop 0
	global_load_lds_dwordx4 v134, s[98:99]
	s_waitcnt vmcnt(8)
	s_waitcnt lgkmcnt(0)
	s_barrier
	v_mfma_f32_16x16x32_bf16 v[124:127], v[148:151], v[180:183], v[124:127]
	v_mfma_f32_16x16x32_bf16 v[120:123], v[156:159], v[180:183], v[120:123]
	v_mfma_f32_16x16x32_bf16 v[108:111], v[148:151], v[188:191], v[108:111]
	v_mfma_f32_16x16x32_bf16 v[104:107], v[156:159], v[188:191], v[104:107]
	v_mfma_f32_16x16x32_bf16 v[92:95], v[148:151], v[196:199], v[92:95]
	v_mfma_f32_16x16x32_bf16 v[88:91], v[156:159], v[196:199], v[88:91]
	v_mfma_f32_16x16x32_bf16 v[76:79], v[148:151], v[206:209], v[76:79]
	v_mfma_f32_16x16x32_bf16 v[72:75], v[156:159], v[206:209], v[72:75]
	v_mfma_f32_16x16x32_bf16 v[124:127], v[152:155], v[184:187], v[124:127]
	v_mfma_f32_16x16x32_bf16 v[120:123], v[160:163], v[184:187], v[120:123]
	v_mfma_f32_16x16x32_bf16 v[108:111], v[152:155], v[192:195], v[108:111]
	v_mfma_f32_16x16x32_bf16 v[104:107], v[160:163], v[192:195], v[104:107]
	v_mfma_f32_16x16x32_bf16 v[92:95], v[152:155], v[200:203], v[92:95]
	v_mfma_f32_16x16x32_bf16 v[88:91], v[160:163], v[200:203], v[88:91]
	v_mfma_f32_16x16x32_bf16 v[76:79], v[152:155], v[210:213], v[76:79]
	v_mfma_f32_16x16x32_bf16 v[72:75], v[160:163], v[210:213], v[72:75]
	v_mfma_f32_16x16x32_bf16 v[116:119], v[164:167], v[180:183], v[116:119]
	v_mfma_f32_16x16x32_bf16 v[112:115], v[172:175], v[180:183], v[112:115]
	v_mfma_f32_16x16x32_bf16 v[100:103], v[164:167], v[188:191], v[100:103]
	v_mfma_f32_16x16x32_bf16 v[96:99], v[172:175], v[188:191], v[96:99]
	v_mfma_f32_16x16x32_bf16 v[84:87], v[164:167], v[196:199], v[84:87]
	v_mfma_f32_16x16x32_bf16 v[80:83], v[172:175], v[196:199], v[80:83]
	v_mfma_f32_16x16x32_bf16 v[68:71], v[164:167], v[206:209], v[68:71]
	v_mfma_f32_16x16x32_bf16 v[64:67], v[172:175], v[206:209], v[64:67]
	v_mfma_f32_16x16x32_bf16 v[116:119], v[168:171], v[184:187], v[116:119]
	v_mfma_f32_16x16x32_bf16 v[112:115], v[176:179], v[184:187], v[112:115]
	v_mfma_f32_16x16x32_bf16 v[100:103], v[168:171], v[192:195], v[100:103]
	v_mfma_f32_16x16x32_bf16 v[96:99], v[176:179], v[192:195], v[96:99]
	v_mfma_f32_16x16x32_bf16 v[84:87], v[168:171], v[200:203], v[84:87]
	v_mfma_f32_16x16x32_bf16 v[80:83], v[176:179], v[200:203], v[80:83]
	v_mfma_f32_16x16x32_bf16 v[68:71], v[168:171], v[210:213], v[68:71]
	v_mfma_f32_16x16x32_bf16 v[64:67], v[176:179], v[210:213], v[64:67]
	s_barrier
	s_add_i32 s52, s46, s36
	s_mov_b32 m0, s52
	ds_read_b128 v[180:183], v147 offset:16384
	ds_read_b128 v[184:187], v147 offset:17408
	ds_read_b128 v[188:191], v147 offset:18432
	ds_read_b128 v[192:195], v147 offset:19456
	ds_read_b128 v[196:199], v147 offset:20480
	ds_read_b128 v[200:203], v147 offset:21504
	ds_read_b128 v[206:209], v147 offset:22528
	ds_read_b128 v[210:213], v147 offset:23552
	global_load_lds_dwordx4 v130, s[30:31]
	s_add_i32 m0, s52, 0x2000
	s_add_u32 s98, s30, 0x80
	s_addc_u32 s99, s31, 0
	s_add_u32 s52, s30, 0x100000
	s_addc_u32 s53, s31, 0
	s_add_i32 s54, s47, s36
	global_load_lds_dwordx4 v132, s[30:31]
	s_mov_b32 m0, s54
	s_nop 0
	global_load_lds_dwordx4 v130, s[52:53]
	s_add_i32 m0, s54, 0x2000
	s_nop 0
	global_load_lds_dwordx4 v132, s[52:53]
	s_mov_b32 m0, s11
	s_nop 0
	global_load_lds_dwordx4 v130, s[34:35]
	s_mov_b32 m0, s37
	s_nop 0
	global_load_lds_dwordx4 v132, s[34:35]
	s_waitcnt vmcnt(8)
	s_waitcnt lgkmcnt(0)
	s_barrier
	v_mfma_f32_16x16x32_bf16 v[60:63], v[148:151], v[180:183], v[60:63]
	v_mfma_f32_16x16x32_bf16 v[56:59], v[156:159], v[180:183], v[56:59]
	v_mfma_f32_16x16x32_bf16 v[44:47], v[148:151], v[188:191], v[44:47]
	v_mfma_f32_16x16x32_bf16 v[40:43], v[156:159], v[188:191], v[40:43]
	v_mfma_f32_16x16x32_bf16 v[28:31], v[148:151], v[196:199], v[28:31]
	v_mfma_f32_16x16x32_bf16 v[24:27], v[156:159], v[196:199], v[24:27]
	v_mfma_f32_16x16x32_bf16 v[12:15], v[148:151], v[206:209], v[12:15]
	v_mfma_f32_16x16x32_bf16 v[8:11], v[156:159], v[206:209], v[8:11]
	v_mfma_f32_16x16x32_bf16 v[60:63], v[152:155], v[184:187], v[60:63]
	v_mfma_f32_16x16x32_bf16 v[56:59], v[160:163], v[184:187], v[56:59]
	v_mfma_f32_16x16x32_bf16 v[44:47], v[152:155], v[192:195], v[44:47]
	v_mfma_f32_16x16x32_bf16 v[40:43], v[160:163], v[192:195], v[40:43]
	v_mfma_f32_16x16x32_bf16 v[28:31], v[152:155], v[200:203], v[28:31]
	v_mfma_f32_16x16x32_bf16 v[24:27], v[160:163], v[200:203], v[24:27]
	v_mfma_f32_16x16x32_bf16 v[12:15], v[152:155], v[210:213], v[12:15]
	v_mfma_f32_16x16x32_bf16 v[8:11], v[160:163], v[210:213], v[8:11]
	v_mfma_f32_16x16x32_bf16 v[52:55], v[164:167], v[180:183], v[52:55]
	v_mfma_f32_16x16x32_bf16 v[48:51], v[172:175], v[180:183], v[48:51]
	v_mfma_f32_16x16x32_bf16 v[36:39], v[164:167], v[188:191], v[36:39]
	v_mfma_f32_16x16x32_bf16 v[32:35], v[172:175], v[188:191], v[32:35]
	v_mfma_f32_16x16x32_bf16 v[20:23], v[164:167], v[196:199], v[20:23]
	v_mfma_f32_16x16x32_bf16 v[16:19], v[172:175], v[196:199], v[16:19]
	v_mfma_f32_16x16x32_bf16 v[4:7], v[164:167], v[206:209], v[4:7]
	v_mfma_f32_16x16x32_bf16 v[0:3], v[172:175], v[206:209], v[0:3]
	v_mfma_f32_16x16x32_bf16 v[52:55], v[168:171], v[184:187], v[52:55]
	v_mfma_f32_16x16x32_bf16 v[48:51], v[176:179], v[184:187], v[48:51]
	v_mfma_f32_16x16x32_bf16 v[36:39], v[168:171], v[192:195], v[36:39]
	v_mfma_f32_16x16x32_bf16 v[32:35], v[176:179], v[192:195], v[32:35]
	v_mfma_f32_16x16x32_bf16 v[20:23], v[168:171], v[200:203], v[20:23]
	v_mfma_f32_16x16x32_bf16 v[16:19], v[176:179], v[200:203], v[16:19]
	v_mfma_f32_16x16x32_bf16 v[4:7], v[168:171], v[210:213], v[4:7]
	v_mfma_f32_16x16x32_bf16 v[0:3], v[176:179], v[210:213], v[0:3]
	s_barrier
; #define PG8_STAGE(bufoff, gbase, voff) do { _Pragma("unroll") for (int _i = 0; _i < 2; ++_i) \
;         __builtin_amdgcn_global_load_lds((const unsigned*)((const char*)(gbase) + (voff)[_i]), (PG8_LAS unsigned*)(lds + (bufoff) + ldsw + _i * 8192), 16, 0, 0); } while (0)
; #define PG8_LDA(dst, b, h) do { _Pragma("unroll") for (int m = 0; m < 4; ++m) _Pragma("unroll") for (int k = 0; k < 2; ++k) dst[m][k] = *(const PG8_LAS bf16x8*)(lds + PG8_SA(b, h) + aoff + m * 2048 + k * 1024); } while (0)
; #define PG8_LDB(dst, b, h) do { _Pragma("unroll") for (int n = 0; n < 2; ++n) _Pragma("unroll") for (int k = 0; k < 2; ++k) dst[n][k] = *(const PG8_LAS bf16x8*)(lds + PG8_SB(b, h) + boff + n * 2048 + k * 1024); } while (0)
; #define PG8_MMA(ai, bj, At, Bt) do { __builtin_amdgcn_s_setprio(1); _Pragma("unroll") for (int m = 0; m < 4; ++m) _Pragma("unroll") for (int n = 0; n < 2; ++n) _Pragma("unroll") for (int k = 0; k < 2; ++k) \
;         acc[ai][bj][m][n] = __builtin_amdgcn_mfma_f32_16x16x32_bf16(Bt[n][k], At[m][k], acc[ai][bj][m][n], 0, 0, 0); __builtin_amdgcn_s_setprio(0); } while (0)
; #define PG8_WAIT_V(n) asm volatile("s_waitcnt vmcnt(" #n ")" ::: "memory")
; #define PG8_WAIT_L(n) asm volatile("s_waitcnt lgkmcnt(" #n ")" ::: "memory")
; #define PG8_BAR __builtin_amdgcn_s_barrier()
; #define PG8_SCHED __builtin_amdgcn_sched_barrier(0)
; template <class Epi, class Sched, bool ALIGN_EPI = false, bool SP2 = false>
; __device__ __forceinline__ void gemm_phase(PG8_LAS unsigned char* lds, const Gemm g, const Sched& S, const Epi& E) {
;     ...
;             PG8_LDB(B0, 1, 0); PG8_LDB(B1, 1, 1); PG8_SCHED; PG8_LDA(At, 1, 0); PG8_STAGE(PG8_SA(0, 1), a2 + hstep, voffA);
;             PG8_WAIT_V(8); PG8_WAIT_L(0); PG8_BAR; PG8_MMA(0, 0, At, B0); PG8_MMA(0, 1, At, B1); PG8_BAR; PG8_SCHED;
;             PG8_LDA(At, 1, 1); PG8_STAGE(PG8_SB(1, 0), b3, voffB); PG8_STAGE(PG8_SB(1, 1), b3 + hstep, voffB); PG8_STAGE(PG8_SA(1, 0), a3, voffA);
;             PG8_WAIT_V(8); PG8_WAIT_L(0); PG8_BAR; PG8_MMA(1, 0, At, B0); PG8_MMA(1, 1, At, B1); PG8_BAR; PG8_SCHED;
	s_add_i32 s52, 0, 0x18000
	s_add_i32 s53, 0, 0x1c000
	ds_read_b128 v[148:151], v242
	ds_read_b128 v[152:155], v242 offset:1024
	ds_read_b128 v[156:159], v242 offset:2048
	ds_read_b128 v[160:163], v242 offset:3072
	ds_read_b128 v[164:167], v243
	ds_read_b128 v[168:171], v243 offset:1024
	ds_read_b128 v[172:175], v243 offset:2048
	ds_read_b128 v[176:179], v243 offset:3072
	s_add_u32 s100, s34, 0x80
	s_addc_u32 s101, s35, 0
	s_add_u32 s34, s34, 0x100000
	s_addc_u32 s35, s35, 0
	s_mov_b32 m0, s38
	ds_read_b128 v[180:183], v147 offset:32768
	ds_read_b128 v[184:187], v147 offset:33792
	ds_read_b128 v[188:191], v147 offset:34816
	ds_read_b128 v[192:195], v147 offset:35840
	ds_read_b128 v[196:199], v147 offset:36864
	ds_read_b128 v[200:203], v147 offset:37888
	ds_read_b128 v[206:209], v147 offset:38912
	ds_read_b128 v[210:213], v147 offset:39936
	global_load_lds_dwordx4 v130, s[34:35]
	s_mov_b32 m0, s40
	s_nop 0
	global_load_lds_dwordx4 v132, s[34:35]
	s_waitcnt vmcnt(8)
	s_waitcnt lgkmcnt(0)
	s_barrier
	v_mfma_f32_16x16x32_bf16 v[124:127], v[148:151], v[180:183], v[124:127]
	v_mfma_f32_16x16x32_bf16 v[120:123], v[156:159], v[180:183], v[120:123]
	v_mfma_f32_16x16x32_bf16 v[108:111], v[148:151], v[188:191], v[108:111]
	v_mfma_f32_16x16x32_bf16 v[104:107], v[156:159], v[188:191], v[104:107]
	v_mfma_f32_16x16x32_bf16 v[92:95], v[148:151], v[196:199], v[92:95]
	v_mfma_f32_16x16x32_bf16 v[88:91], v[156:159], v[196:199], v[88:91]
	v_mfma_f32_16x16x32_bf16 v[76:79], v[148:151], v[206:209], v[76:79]
	v_mfma_f32_16x16x32_bf16 v[72:75], v[156:159], v[206:209], v[72:75]
	v_mfma_f32_16x16x32_bf16 v[124:127], v[152:155], v[184:187], v[124:127]
	v_mfma_f32_16x16x32_bf16 v[120:123], v[160:163], v[184:187], v[120:123]
	v_mfma_f32_16x16x32_bf16 v[108:111], v[152:155], v[192:195], v[108:111]
	v_mfma_f32_16x16x32_bf16 v[104:107], v[160:163], v[192:195], v[104:107]
	v_mfma_f32_16x16x32_bf16 v[92:95], v[152:155], v[200:203], v[92:95]
	v_mfma_f32_16x16x32_bf16 v[88:91], v[160:163], v[200:203], v[88:91]
	v_mfma_f32_16x16x32_bf16 v[76:79], v[152:155], v[210:213], v[76:79]
	v_mfma_f32_16x16x32_bf16 v[72:75], v[160:163], v[210:213], v[72:75]
	v_mfma_f32_16x16x32_bf16 v[116:119], v[164:167], v[180:183], v[116:119]
	v_mfma_f32_16x16x32_bf16 v[112:115], v[172:175], v[180:183], v[112:115]
	v_mfma_f32_16x16x32_bf16 v[100:103], v[164:167], v[188:191], v[100:103]
	v_mfma_f32_16x16x32_bf16 v[96:99], v[172:175], v[188:191], v[96:99]
	v_mfma_f32_16x16x32_bf16 v[84:87], v[164:167], v[196:199], v[84:87]
	v_mfma_f32_16x16x32_bf16 v[80:83], v[172:175], v[196:199], v[80:83]
	v_mfma_f32_16x16x32_bf16 v[68:71], v[164:167], v[206:209], v[68:71]
	v_mfma_f32_16x16x32_bf16 v[64:67], v[172:175], v[206:209], v[64:67]
	v_mfma_f32_16x16x32_bf16 v[116:119], v[168:171], v[184:187], v[116:119]
	v_mfma_f32_16x16x32_bf16 v[112:115], v[176:179], v[184:187], v[112:115]
	v_mfma_f32_16x16x32_bf16 v[100:103], v[168:171], v[192:195], v[100:103]
	v_mfma_f32_16x16x32_bf16 v[96:99], v[176:179], v[192:195], v[96:99]
	v_mfma_f32_16x16x32_bf16 v[84:87], v[168:171], v[200:203], v[84:87]
	v_mfma_f32_16x16x32_bf16 v[80:83], v[176:179], v[200:203], v[80:83]
	v_mfma_f32_16x16x32_bf16 v[68:71], v[168:171], v[210:213], v[68:71]
	v_mfma_f32_16x16x32_bf16 v[64:67], v[176:179], v[210:213], v[64:67]
	s_barrier
	s_add_i32 s34, s52, s36
	s_mov_b32 m0, s34
	ds_read_b128 v[180:183], v147 offset:49152
	ds_read_b128 v[184:187], v147 offset:50176
	ds_read_b128 v[188:191], v147 offset:51200
	ds_read_b128 v[192:195], v147 offset:52224
	ds_read_b128 v[196:199], v147 offset:53248
	ds_read_b128 v[200:203], v147 offset:54272
	ds_read_b128 v[206:209], v147 offset:55296
	ds_read_b128 v[210:213], v147 offset:56320
	global_load_lds_dwordx4 v130, s[98:99]
	s_add_i32 m0, s34, 0x2000
	s_add_u32 s30, s30, 0x100080
	s_addc_u32 s31, s31, 0
	s_add_i32 s34, s53, s36
	global_load_lds_dwordx4 v132, s[98:99]
	s_mov_b32 m0, s34
	s_nop 0
	global_load_lds_dwordx4 v130, s[30:31]
	s_add_i32 m0, s34, 0x2000
	s_nop 0
	global_load_lds_dwordx4 v132, s[30:31]
	s_mov_b32 m0, s42
	s_nop 0
	global_load_lds_dwordx4 v130, s[100:101]
	s_mov_b32 m0, s43
	s_nop 0
	global_load_lds_dwordx4 v132, s[100:101]
	s_waitcnt vmcnt(8)
	s_waitcnt lgkmcnt(0)
	s_barrier
; #define PG8_MMA(ai, bj, At, Bt) do { __builtin_amdgcn_s_setprio(1); _Pragma("unroll") for (int m = 0; m < 4; ++m) _Pragma("unroll") for (int n = 0; n < 2; ++n) _Pragma("unroll") for (int k = 0; k < 2; ++k) \
;         acc[ai][bj][m][n] = __builtin_amdgcn_mfma_f32_16x16x32_bf16(Bt[n][k], At[m][k], acc[ai][bj][m][n], 0, 0, 0); __builtin_amdgcn_s_setprio(0); } while (0)
; #define PG8_WAIT_V(n) asm volatile("s_waitcnt vmcnt(" #n ")" ::: "memory")
; #define PG8_WAIT_L(n) asm volatile("s_waitcnt lgkmcnt(" #n ")" ::: "memory")
; #define PG8_BAR __builtin_amdgcn_s_barrier()
; #define PG8_SCHED __builtin_amdgcn_sched_barrier(0)
; template <class Epi, class Sched, bool ALIGN_EPI = false, bool SP2 = false>
; __device__ __forceinline__ void gemm_phase(PG8_LAS unsigned char* lds, const Gemm g, const Sched& S, const Epi& E) {
;     ...
;             PG8_WAIT_V(8); PG8_WAIT_L(0); PG8_BAR; PG8_MMA(1, 0, At, B0); PG8_MMA(1, 1, At, B1); PG8_BAR; PG8_SCHED;
;     ...
;         if (!has_next) break;
; #pragma unroll
;         for (int a = 0; a < 2; ++a)
; #pragma unroll
;             for (int b = 0; b < 2; ++b)
; #pragma unroll
;                 for (int m = 0; m < 4; ++m)
; #pragma unroll
;                     for (int n = 0; n < 2; ++n) acc[a][b][m][n] = (f32x4){0.f, 0.f, 0.f, 0.f};
;         cur = nxt; cA = nA; cB = nB; ++ui;
	v_mfma_f32_16x16x32_bf16 v[60:63], v[148:151], v[180:183], v[60:63]
	v_mfma_f32_16x16x32_bf16 v[56:59], v[156:159], v[180:183], v[56:59]
	v_mfma_f32_16x16x32_bf16 v[44:47], v[148:151], v[188:191], v[44:47]
	v_mfma_f32_16x16x32_bf16 v[40:43], v[156:159], v[188:191], v[40:43]
	v_mfma_f32_16x16x32_bf16 v[28:31], v[148:151], v[196:199], v[28:31]
	v_mfma_f32_16x16x32_bf16 v[24:27], v[156:159], v[196:199], v[24:27]
	v_mfma_f32_16x16x32_bf16 v[12:15], v[148:151], v[206:209], v[12:15]
	v_mfma_f32_16x16x32_bf16 v[8:11], v[156:159], v[206:209], v[8:11]
	v_mfma_f32_16x16x32_bf16 v[60:63], v[152:155], v[184:187], v[60:63]
	v_mfma_f32_16x16x32_bf16 v[56:59], v[160:163], v[184:187], v[56:59]
	v_mfma_f32_16x16x32_bf16 v[44:47], v[152:155], v[192:195], v[44:47]
	v_mfma_f32_16x16x32_bf16 v[40:43], v[160:163], v[192:195], v[40:43]
	v_mfma_f32_16x16x32_bf16 v[28:31], v[152:155], v[200:203], v[28:31]
	v_mfma_f32_16x16x32_bf16 v[24:27], v[160:163], v[200:203], v[24:27]
	v_mfma_f32_16x16x32_bf16 v[12:15], v[152:155], v[210:213], v[12:15]
	v_mfma_f32_16x16x32_bf16 v[8:11], v[160:163], v[210:213], v[8:11]
	v_mfma_f32_16x16x32_bf16 v[52:55], v[164:167], v[180:183], v[52:55]
	v_mfma_f32_16x16x32_bf16 v[48:51], v[172:175], v[180:183], v[48:51]
	v_mfma_f32_16x16x32_bf16 v[36:39], v[164:167], v[188:191], v[36:39]
	v_mfma_f32_16x16x32_bf16 v[32:35], v[172:175], v[188:191], v[32:35]
	v_mfma_f32_16x16x32_bf16 v[20:23], v[164:167], v[196:199], v[20:23]
	v_mfma_f32_16x16x32_bf16 v[16:19], v[172:175], v[196:199], v[16:19]
	v_mfma_f32_16x16x32_bf16 v[4:7], v[164:167], v[206:209], v[4:7]
	v_mfma_f32_16x16x32_bf16 v[0:3], v[172:175], v[206:209], v[0:3]
	v_mfma_f32_16x16x32_bf16 v[52:55], v[168:171], v[184:187], v[52:55]
	v_mfma_f32_16x16x32_bf16 v[48:51], v[176:179], v[184:187], v[48:51]
	v_mfma_f32_16x16x32_bf16 v[36:39], v[168:171], v[192:195], v[36:39]
	v_mfma_f32_16x16x32_bf16 v[32:35], v[176:179], v[192:195], v[32:35]
	v_mfma_f32_16x16x32_bf16 v[20:23], v[168:171], v[200:203], v[20:23]
	v_mfma_f32_16x16x32_bf16 v[16:19], v[176:179], v[200:203], v[16:19]
	v_mfma_f32_16x16x32_bf16 v[4:7], v[168:171], v[210:213], v[4:7]
	v_mfma_f32_16x16x32_bf16 v[0:3], v[176:179], v[210:213], v[0:3]
	s_barrier
	s_add_i32 s51, s51, 2
	s_add_u32 s28, s28, 0x100
	s_addc_u32 s29, s29, 0
	s_cmp_gt_u32 s51, 61
	s_cbranch_scc0 .LBB0_1025
	s_add_u32 s28, s25, 0xffffff00
	s_addc_u32 s29, s48, -1
	s_andn2_b64 vcc, exec, s[6:7]
	s_cbranch_vccnz .LBB0_1028
	v_mov_b32_e32 v0, 0
	s_mov_b32 s44, s18
	s_mov_b32 s10, s20
	s_mov_b64 s[12:13], s[26:27]
	s_mov_b32 s45, s24
	v_mov_b32_e32 v1, v0
	v_mov_b32_e32 v2, v0
	v_mov_b32_e32 v3, v0
	v_mov_b32_e32 v4, v0
	v_mov_b32_e32 v5, v0
	v_mov_b32_e32 v6, v0
	v_mov_b32_e32 v7, v0
	v_mov_b32_e32 v16, v0
	v_mov_b32_e32 v17, v0
	v_mov_b32_e32 v18, v0
	v_mov_b32_e32 v19, v0
	v_mov_b32_e32 v20, v0
	v_mov_b32_e32 v21, v0
	v_mov_b32_e32 v22, v0
	v_mov_b32_e32 v23, v0
	v_mov_b32_e32 v32, v0
	v_mov_b32_e32 v33, v0
	v_mov_b32_e32 v34, v0
	v_mov_b32_e32 v35, v0
	v_mov_b32_e32 v36, v0
	v_mov_b32_e32 v37, v0
	v_mov_b32_e32 v38, v0
	v_mov_b32_e32 v39, v0
	v_mov_b32_e32 v48, v0
	v_mov_b32_e32 v49, v0
	v_mov_b32_e32 v50, v0
	v_mov_b32_e32 v51, v0
	v_mov_b32_e32 v52, v0
	v_mov_b32_e32 v53, v0
	v_mov_b32_e32 v54, v0
	v_mov_b32_e32 v55, v0
	v_mov_b32_e32 v8, v0
	v_mov_b32_e32 v9, v0
	v_mov_b32_e32 v10, v0
	v_mov_b32_e32 v11, v0
	v_mov_b32_e32 v12, v0
	v_mov_b32_e32 v13, v0
	v_mov_b32_e32 v14, v0
	v_mov_b32_e32 v15, v0
	v_mov_b32_e32 v24, v0
	v_mov_b32_e32 v25, v0
	v_mov_b32_e32 v26, v0
	v_mov_b32_e32 v27, v0
	v_mov_b32_e32 v28, v0
	v_mov_b32_e32 v29, v0
	v_mov_b32_e32 v30, v0
	v_mov_b32_e32 v31, v0
	v_mov_b32_e32 v40, v0
	v_mov_b32_e32 v41, v0
	v_mov_b32_e32 v42, v0
	v_mov_b32_e32 v43, v0
	v_mov_b32_e32 v44, v0
	v_mov_b32_e32 v45, v0
	v_mov_b32_e32 v46, v0
	v_mov_b32_e32 v47, v0
	v_mov_b32_e32 v56, v0
	v_mov_b32_e32 v57, v0
	v_mov_b32_e32 v58, v0
	v_mov_b32_e32 v59, v0
	v_mov_b32_e32 v60, v0
	v_mov_b32_e32 v61, v0
	v_mov_b32_e32 v62, v0
	v_mov_b32_e32 v63, v0
	v_mov_b32_e32 v64, v0
	v_mov_b32_e32 v65, v0
	v_mov_b32_e32 v66, v0
	v_mov_b32_e32 v67, v0
	v_mov_b32_e32 v68, v0
	v_mov_b32_e32 v69, v0
	v_mov_b32_e32 v70, v0
	v_mov_b32_e32 v71, v0
	v_mov_b32_e32 v80, v0
	v_mov_b32_e32 v81, v0
	v_mov_b32_e32 v82, v0
	v_mov_b32_e32 v83, v0
	v_mov_b32_e32 v84, v0
	v_mov_b32_e32 v85, v0
	v_mov_b32_e32 v86, v0
	v_mov_b32_e32 v87, v0
	v_mov_b32_e32 v96, v0
	v_mov_b32_e32 v97, v0
	v_mov_b32_e32 v98, v0
	v_mov_b32_e32 v99, v0
	v_mov_b32_e32 v100, v0
	v_mov_b32_e32 v101, v0
	v_mov_b32_e32 v102, v0
	v_mov_b32_e32 v103, v0
	v_mov_b32_e32 v112, v0
	v_mov_b32_e32 v113, v0
	v_mov_b32_e32 v114, v0
	v_mov_b32_e32 v115, v0
	v_mov_b32_e32 v116, v0
	v_mov_b32_e32 v117, v0
	v_mov_b32_e32 v118, v0
	v_mov_b32_e32 v119, v0
	v_mov_b32_e32 v72, v0
	v_mov_b32_e32 v73, v0
	v_mov_b32_e32 v74, v0
	v_mov_b32_e32 v75, v0
	v_mov_b32_e32 v76, v0
	v_mov_b32_e32 v77, v0
	v_mov_b32_e32 v78, v0
	v_mov_b32_e32 v79, v0
	v_mov_b32_e32 v88, v0
	v_mov_b32_e32 v89, v0
	v_mov_b32_e32 v90, v0
	v_mov_b32_e32 v91, v0
	v_mov_b32_e32 v92, v0
	v_mov_b32_e32 v93, v0
	v_mov_b32_e32 v94, v0
	v_mov_b32_e32 v95, v0
	v_mov_b32_e32 v104, v0
	v_mov_b32_e32 v105, v0
	v_mov_b32_e32 v106, v0
	v_mov_b32_e32 v107, v0
	v_mov_b32_e32 v108, v0
	v_mov_b32_e32 v109, v0
	v_mov_b32_e32 v110, v0
	v_mov_b32_e32 v111, v0
	v_mov_b32_e32 v120, v0
	v_mov_b32_e32 v121, v0
	v_mov_b32_e32 v122, v0
	v_mov_b32_e32 v123, v0
	v_mov_b32_e32 v124, v0
	v_mov_b32_e32 v125, v0
	v_mov_b32_e32 v126, v0
	v_mov_b32_e32 v127, v0
	s_andn2_b64 vcc, exec, s[0:1]
	s_cbranch_vccnz .LBB0_1029
	s_branch .LBB0_1030
